# speedup vs baseline: 1.0205x; 1.0205x over previous
; DI int my_tid() { int t = threadIdx.x; asm volatile("" : "+v"(t)); return t; }
; #define PEER_SWAP() do { _Pragma("unroll") for (int q_ = 0; q_ < 8; ++q_) _Pragma("unroll") for (int c_ = 0; c_ < 4; ++c_) { \
;             const auto r_ = __builtin_amdgcn_permlane32_swap(ra[q_][c_], rb[q_][c_], false, false); ucur[q_][c_] = r_[0]; vcur[q_][c_] = r_[1]; } } while (0)
; #define PEER_LOADREC_MEM(ep_) do { \
;         _Pragma("unroll") for (int q_ = 0; q_ < 8; ++q_) { \
;             const int ia_ = __builtin_amdgcn_readfirstlane((ep_)[2 * q_]), ib_ = __builtin_amdgcn_readfirstlane((ep_)[2 * q_ + 1]); \
;             ra[q_] = *(const u32x4*)(REC + (size_t)ia_ * 1024); rb[q_] = *(const u32x4*)(REC + (size_t)ib_ * 1024); } } while (0)
; #define PEER_NEXTOPS(t_) do { const u32x4* xr_ = (const u32x4*)(xb + (size_t)(t_) * PA + 32 * l5); xq[0] = xr_[0]; xq[1] = xr_[1]; xq[2] = xr_[2]; xq[3] = xr_[3]; \
;         ivq0 = eidx[(size_t)(t_) * 128 + lane]; ivq1 = eidx[(size_t)(t_) * 128 + 64 + lane]; gvq0 = gate[(size_t)(t_) * 128 + lane]; gvq1 = gate[(size_t)(t_) * 128 + 64 + lane]; } while (0)
; DI void peer_phase(const Params& p, int layer, bool dry) {
;     ...
;     const int lane = my_tid() & 63, wid = __builtin_amdgcn_readfirstlane(my_tid() >> 6);
;     const int gw = blockIdx.x * NWV + wid, nw = gridDim.x * NWV;
;     const unsigned char* U6 = ws + OFF_U; const float* SU = (const float*)(ws + OFF_U + 16777216);
;     const unsigned char* V6 = ws + OFF_V; const float* SV = (const float*)(ws + OFF_V + 16777216);
;     bf16_t* xb = (bf16_t*)(ws + OFF_R2);
;     const float* x1f = (const float*)(ws + OFF_R3);
;     const int* eidx = (const int*)(ws + OFF_EIDX);
;     const float* gate = (const float*)(ws + OFF_GATE);
;     const float* g2 = p.in[16] + layer * DM;
;     const float* b2 = p.in[17] + layer * DM;
;     const int hi = lane >> 5, l5 = lane & 31, b4 = (lane >> 4) & 1, b3 = (lane >> 3) & 1, esel = 4 * b4 + 2 * b3 + hi;
;     u32x4 ucur[8], vcur[8], ra[8], rb[8];
;     const int b2_ = (lane >> 2) & 1, esel16 = 8 * b4 + 4 * b3 + 2 * b2_ + hi;
;     const unsigned char* REC = ws + OFF_U + 16 * lane;
;     ...
;     if (gw < T_TOK) {
;         PEER_LOADREC_MEM(eidx + (size_t)gw * 128);
;         PEER_SWAP();
;     }
;     u32x4 xq[4]; int ivq0 = 0, ivq1 = 0; float gvq0 = 0.f, gvq1 = 0.f;
;     ...
;     if (gw < T_TOK) PEER_NEXTOPS(gw);
.LBB0_28:
	v_readlane_b32 s0, v252, 34
	s_ashr_i32 s42, s0, 3
	s_and_b32 s28, s0, 7
	s_cmp_lt_u32 s0, 8
	v_readlane_b32 s1, v252, 35
	s_cselect_b64 s[2:3], -1, 0
	s_cmp_gt_u32 s0, 7
	v_writelane_b32 v250, s2, 21
	s_cselect_b64 s[12:13], -1, 0
	s_cmp_lt_i32 s28, 4
	s_mov_b64 s[0:1], -1
	v_writelane_b32 v250, s3, 22
	s_cbranch_scc1 .LBB0_130
	s_lshl_b32 s14, s42, 10
	s_ashr_i32 s15, s14, 31
	s_cmp_lt_i32 s28, 6
	s_cbranch_scc1 .LBB0_85
	s_cmp_gt_i32 s28, 6
	s_cbranch_scc0 .LBB0_51
	v_mov_b32_e32 v80, v192
	v_mov_b32_e32 v0, v192
	v_readlane_b32 s1, v252, 36
	v_readfirstlane_b32 s0, v0
	s_ashr_i32 s0, s0, 6
	s_mul_i32 s32, s0, 0x4100
	s_lshl_b32 s45, s0, 11
	s_add_i32 s45, s45, 0x20800
	v_writelane_b32 v250, s45, 42
	s_add_i32 s10, s0, s1
	s_mov_b32 s43, s28
	s_cmpk_gt_i32 s10, 0x7fff
	s_cbranch_scc1 .LBB0_50
	s_waitcnt vmcnt(0)
	v_and_b32_e32 v96, 63, v80
	v_readlane_b32 s0, v252, 37
	v_readlane_b32 s16, v250, 1
	v_lshlrev_b32_e32 v128, 4, v96
	v_lshlrev_b32_e32 v232, 4, v96
	v_lshrrev_b32_e32 v233, 5, v96
	v_mul_u32_u24_e32 v233, 0x410, v233
	v_and_b32_e32 v196, 31, v96
	v_readlane_b32 s12, v252, 37
	v_lshl_add_u32 v233, v196, 4, v233
	v_readlane_b32 s13, v252, 38
	v_add_u32_e32 v233, s32, v233
	v_and_b32_e32 v196, 15, v96
	v_mul_u32_u24_e32 v196, 0x410, v196
	v_lshrrev_b32_e32 v210, 4, v96
	v_lshl_add_u32 v196, v210, 4, v196
	v_add_u32_e32 v196, s32, v196
	v_lshlrev_b32_e32 v210, 6, v210
	v_add_u32_e32 v210, s45, v210
	v_readlane_b32 s1, v252, 38
	s_lshl_b64 s[2:3], s[14:15], 2
	v_readlane_b32 s18, v250, 3
	v_lshl_add_u64 v[98:99], s[0:1], 0, v[128:129]
	v_readlane_b32 s19, v250, 4
	s_add_u32 s0, s18, s2
	s_addc_u32 s1, s19, s3
	v_readlane_b32 s17, v250, 2
	s_add_u32 s18, s16, s2
	s_addc_u32 s19, s17, s3
	s_cmp_eq_u32 s42, 1
	s_cselect_b64 s[16:17], -1, 0
	s_ashr_i32 s11, s10, 31
	s_lshl_b64 s[2:3], s[10:11], 9
	v_bfe_u32 v85, v80, 4, 1
	v_bfe_u32 v84, v80, 3, 1
	v_bfe_u32 v83, v80, 2, 1
	s_add_u32 s4, s92, s2
	v_lshlrev_b32_e32 v0, 3, v85
	v_lshlrev_b32_e32 v1, 2, v84
	v_lshlrev_b32_e32 v2, 1, v83
	s_addc_u32 s5, s93, s3
	v_or3_b32 v81, v0, v1, v2
	global_load_dwordx4 v[0:3], v129, s[4:5] offset:48
	global_load_dwordx4 v[4:7], v129, s[4:5] offset:32
	global_load_dwordx4 v[8:11], v129, s[4:5] offset:16
	global_load_dwordx4 v[12:15], v129, s[4:5]
	v_lshlrev_b32_e32 v64, 5, v80
	v_and_b32_e32 v92, 0x3e0, v64
	v_lshl_or_b32 v86, v96, 2, s2
	v_mov_b32_e32 v87, s3
	v_lshlrev_b32_e32 v128, 1, v92
	v_lshl_add_u64 v[88:89], s[92:93], 0, v[86:87]
	v_cmp_lt_i32_e32 vcc, v199, v200
	v_bfe_u32 v82, v80, 5, 1
	v_lshl_add_u64 v[100:101], s[88:89], 0, v[128:129]
	v_and_or_b32 v80, v80, 32, v198
	v_readlane_b32 s20, v250, 5
	v_readlane_b32 s21, v250, 6
	v_lshrrev_b32_e32 v216, 3, v80
	v_cmp_gt_u32_e64 s[8:9], 32, v96
	v_or_b32_e32 v217, 8, v216
	v_or_b32_e32 v219, 16, v216
	v_or_b32_e32 v220, 24, v216
	v_or_b32_e32 v221, 32, v216
	v_or_b32_e32 v222, 40, v216
	v_or_b32_e32 v223, 48, v216
	v_or_b32_e32 v224, 56, v216
	v_readlane_b32 s22, v250, 7
	v_readlane_b32 s23, v250, 8
	s_waitcnt vmcnt(0)
; #define PEER_SWAP() do { _Pragma("unroll") for (int q_ = 0; q_ < 8; ++q_) _Pragma("unroll") for (int c_ = 0; c_ < 4; ++c_) { \
;             const auto r_ = __builtin_amdgcn_permlane32_swap(ra[q_][c_], rb[q_][c_], false, false); ucur[q_][c_] = r_[0]; vcur[q_][c_] = r_[1]; } } while (0)
; #define PEER_LOADREC_MEM(ep_) do { \
;         _Pragma("unroll") for (int q_ = 0; q_ < 8; ++q_) { \
;             const int ia_ = __builtin_amdgcn_readfirstlane((ep_)[2 * q_]), ib_ = __builtin_amdgcn_readfirstlane((ep_)[2 * q_ + 1]); \
;             ra[q_] = *(const u32x4*)(REC + (size_t)ia_ * 1024); rb[q_] = *(const u32x4*)(REC + (size_t)ib_ * 1024); } } while (0)
; #define PEER_NEXTOPS(t_) do { const u32x4* xr_ = (const u32x4*)(xb + (size_t)(t_) * PA + 32 * l5); xq[0] = xr_[0]; xq[1] = xr_[1]; xq[2] = xr_[2]; xq[3] = xr_[3]; \
;         ivq0 = eidx[(size_t)(t_) * 128 + lane]; ivq1 = eidx[(size_t)(t_) * 128 + 64 + lane]; gvq0 = gate[(size_t)(t_) * 128 + lane]; gvq1 = gate[(size_t)(t_) * 128 + 64 + lane]; } while (0)
; DI void peer_phase(const Params& p, int layer, bool dry) {
;     ...
;     if (gw < T_TOK) {
;         PEER_LOADREC_MEM(eidx + (size_t)gw * 128);
;         PEER_SWAP();
;     }
;     u32x4 xq[4]; int ivq0 = 0, ivq1 = 0; float gvq0 = 0.f, gvq1 = 0.f;
;     ...
;     if (gw < T_TOK) PEER_NEXTOPS(gw);
	v_readfirstlane_b32 s44, v12
	s_mov_b32 m0, s32
	s_lshl_b32 s44, s44, 10
	s_add_u32 s44, s12, s44
	s_addc_u32 s45, s13, 0
	global_load_lds_dwordx4 v232, s[44:45] sc1
	v_readfirstlane_b32 s44, v13
	s_add_i32 m0, s32, 0x410
	s_lshl_b32 s44, s44, 10
	s_add_u32 s44, s12, s44
	s_addc_u32 s45, s13, 0
	global_load_lds_dwordx4 v232, s[44:45] sc1
	v_readfirstlane_b32 s44, v14
	s_add_i32 m0, s32, 0x820
	s_lshl_b32 s44, s44, 10
	s_add_u32 s44, s12, s44
	s_addc_u32 s45, s13, 0
	global_load_lds_dwordx4 v232, s[44:45] sc1
	v_readfirstlane_b32 s44, v15
	s_add_i32 m0, s32, 0xc30
	s_lshl_b32 s44, s44, 10
	s_add_u32 s44, s12, s44
	s_addc_u32 s45, s13, 0
	global_load_lds_dwordx4 v232, s[44:45] sc1
	v_readfirstlane_b32 s44, v8
	s_add_i32 m0, s32, 0x1040
	s_lshl_b32 s44, s44, 10
	s_add_u32 s44, s12, s44
	s_addc_u32 s45, s13, 0
	global_load_lds_dwordx4 v232, s[44:45] sc1
	v_readfirstlane_b32 s44, v9
	s_add_i32 m0, s32, 0x1450
	s_lshl_b32 s44, s44, 10
	s_add_u32 s44, s12, s44
	s_addc_u32 s45, s13, 0
	global_load_lds_dwordx4 v232, s[44:45] sc1
	v_readfirstlane_b32 s44, v10
	s_add_i32 m0, s32, 0x1860
	s_lshl_b32 s44, s44, 10
	s_add_u32 s44, s12, s44
	s_addc_u32 s45, s13, 0
	global_load_lds_dwordx4 v232, s[44:45] sc1
	v_readfirstlane_b32 s44, v11
	s_add_i32 m0, s32, 0x1c70
	s_lshl_b32 s44, s44, 10
	s_add_u32 s44, s12, s44
	s_addc_u32 s45, s13, 0
	global_load_lds_dwordx4 v232, s[44:45] sc1
	v_readfirstlane_b32 s44, v4
	s_add_i32 m0, s32, 0x2080
	s_lshl_b32 s44, s44, 10
	s_add_u32 s44, s12, s44
	s_addc_u32 s45, s13, 0
	global_load_lds_dwordx4 v232, s[44:45] sc1
	v_readfirstlane_b32 s44, v5
	s_add_i32 m0, s32, 0x2490
	s_lshl_b32 s44, s44, 10
	s_add_u32 s44, s12, s44
	s_addc_u32 s45, s13, 0
	global_load_lds_dwordx4 v232, s[44:45] sc1
	v_readfirstlane_b32 s44, v6
	s_add_i32 m0, s32, 0x28a0
	s_lshl_b32 s44, s44, 10
	s_add_u32 s44, s12, s44
	s_addc_u32 s45, s13, 0
	global_load_lds_dwordx4 v232, s[44:45] sc1
	v_readfirstlane_b32 s44, v7
	s_add_i32 m0, s32, 0x2cb0
	s_lshl_b32 s44, s44, 10
	s_add_u32 s44, s12, s44
	s_addc_u32 s45, s13, 0
	global_load_lds_dwordx4 v232, s[44:45] sc1
	v_readfirstlane_b32 s44, v0
	s_add_i32 m0, s32, 0x30c0
	s_lshl_b32 s44, s44, 10
	s_add_u32 s44, s12, s44
	s_addc_u32 s45, s13, 0
	global_load_lds_dwordx4 v232, s[44:45] sc1
	v_readfirstlane_b32 s44, v1
	s_add_i32 m0, s32, 0x34d0
	s_lshl_b32 s44, s44, 10
	s_add_u32 s44, s12, s44
	s_addc_u32 s45, s13, 0
	global_load_lds_dwordx4 v232, s[44:45] sc1
	v_readfirstlane_b32 s44, v2
	s_add_i32 m0, s32, 0x38e0
	s_lshl_b32 s44, s44, 10
	s_add_u32 s44, s12, s44
	s_addc_u32 s45, s13, 0
	global_load_lds_dwordx4 v232, s[44:45] sc1
	v_readfirstlane_b32 s44, v3
	s_add_i32 m0, s32, 0x3cf0
	s_lshl_b32 s44, s44, 10
	s_add_u32 s44, s12, s44
	s_addc_u32 s45, s13, 0
	global_load_lds_dwordx4 v232, s[44:45] sc1
	s_lshl_b64 s[4:5], s[10:11], 11
	s_add_u32 s4, s88, s4
	s_addc_u32 s5, s89, s5
	global_load_dwordx4 v[64:67], v128, s[4:5] offset:48
	global_load_dwordx4 v[72:75], v128, s[4:5] offset:32
	global_load_dwordx4 v[68:71], v128, s[4:5] offset:16
	global_load_dwordx4 v[76:79], v128, s[4:5]
	global_load_dword v218, v[88:89], off
	v_or_b32_e32 v88, 0x100, v86
	v_mov_b32_e32 v89, s3
	v_lshl_add_u64 v[90:91], s[92:93], 0, v[88:89]
	v_lshl_add_u64 v[86:87], s[76:77], 0, v[86:87]
	global_load_dword v225, v[90:91], off
	global_load_dword v226, v[86:87], off
	v_lshl_add_u64 v[86:87], s[76:77], 0, v[88:89]
	global_load_dword v227, v[86:87], off
	v_cmp_eq_u32_e64 s[2:3], 0, v85
	v_cndmask_b32_e32 v85, v197, v199, vcc
	v_cmp_lt_i32_e32 vcc, v201, v200
	v_cmp_eq_u32_e64 s[4:5], 0, v84
	v_cmp_eq_u32_e64 s[6:7], 0, v83
	v_cndmask_b32_e32 v84, v197, v201, vcc
	v_cmp_lt_i32_e32 vcc, v202, v200
	v_lshlrev_b32_e32 v97, 2, v85
	v_lshlrev_b32_e32 v211, 2, v84
	v_cndmask_b32_e32 v83, v197, v202, vcc
	v_cmp_lt_i32_e32 vcc, v203, v200
	v_lshlrev_b32_e32 v212, 2, v83
	v_mov_b32_e32 v85, v129
	v_cndmask_b32_e32 v83, v197, v203, vcc
	v_cmp_lt_i32_e32 vcc, v204, v200
	v_lshlrev_b32_e32 v213, 2, v83
	v_cndmask_b32_e32 v83, v197, v204, vcc
	v_cmp_lt_i32_e32 vcc, v205, v200
	v_lshlrev_b32_e32 v214, 2, v83
	v_cndmask_b32_e32 v83, v197, v205, vcc
	v_lshlrev_b32_e32 v215, 2, v83
	v_lshl_or_b32 v83, v82, 4, v92
	v_lshlrev_b32_e32 v128, 2, v83
	v_lshl_add_u64 v[104:105], s[0:1], 0, v[128:129]
	v_readlane_b32 s0, v252, 39
	v_lshlrev_b32_e32 v84, 1, v83
	v_readlane_b32 s1, v252, 40
	v_lshl_add_u64 v[102:103], s[18:19], 0, v[128:129]
	v_lshl_add_u64 v[106:107], s[88:89], 0, v[84:85]
	v_lshl_add_u64 v[108:109], s[0:1], 0, v[84:85]
	v_lshl_add_u64 v[110:111], s[20:21], 0, v[128:129]
	v_and_b32_e32 v128, 15, v96
	s_waitcnt vmcnt(8)
	ds_read_b128 v[60:63], v196
	ds_read_b128 v[28:31], v233 offset:512
	ds_read_b128 v[56:59], v196 offset:64
	ds_read_b128 v[24:27], v233 offset:2592
	ds_read_b128 v[52:55], v196 offset:128
	ds_read_b128 v[20:23], v233 offset:4672
	ds_read_b128 v[48:51], v196 offset:192
	ds_read_b128 v[16:19], v233 offset:6752
	ds_read_b128 v[44:47], v196 offset:256
	ds_read_b128 v[12:15], v233 offset:8832
	ds_read_b128 v[40:43], v196 offset:320
	ds_read_b128 v[8:11], v233 offset:10912
	ds_read_b128 v[36:39], v196 offset:384
	ds_read_b128 v[4:7], v233 offset:12992
	ds_read_b128 v[32:35], v196 offset:448
	ds_read_b128 v[0:3], v233 offset:15072
	s_waitcnt lgkmcnt(0)
	global_load_dwordx4 v[234:237], v[102:103], off
	global_load_dwordx4 v[238:241], v[102:103], off offset:16
	global_load_dwordx4 v[242:245], v[102:103], off offset:32
	global_load_dwordx4 v[246:249], v[102:103], off offset:48
	global_load_dwordx4 v[130:133], v[104:105], off
	global_load_dwordx4 v[134:137], v[104:105], off offset:16
	global_load_dwordx4 v[138:141], v[104:105], off offset:32
	global_load_dwordx4 v[206:209], v[104:105], off offset:48
	s_branch .LBB0_34

; DI float bflo(unsigned w) { return __uint_as_float(w << 16); }
; DI float bfhi(unsigned w) { return __uint_as_float(w & 0xffff0000u); }
; DI float dotU(const URow& q, const f32x2 (&x2)[16]) { return dot32r(dec6(q), x2); }
; DI float dotU(const URow& q, const f32x2 (&x2)[16]) {
;     f32x2 a0 = {0.f, 0.f}, a1 = {0.f, 0.f};
; #pragma unroll
;     for (int d = 0; d < 4; ++d) {
;         a0 += __builtin_amdgcn_cvt_scalef32_pk_f32_fp4(q[d], 1.0f, 0) * x2[4 * d];     a1 += __builtin_amdgcn_cvt_scalef32_pk_f32_fp4(q[d], 1.0f, 1) * x2[4 * d + 1];
;         a0 += __builtin_amdgcn_cvt_scalef32_pk_f32_fp4(q[d], 1.0f, 2) * x2[4 * d + 2]; a1 += __builtin_amdgcn_cvt_scalef32_pk_f32_fp4(q[d], 1.0f, 3) * x2[4 * d + 3];
;     }
;     a0 += a1;
;     return a0.x + a0.y;
; }
; DI void peer_phase(const Params& p, int layer, bool dry) {
;     ...
;     for (int t = gw; t < T_TOK; t += nw) {
;         const int tn = (t + nw < T_TOK) ? t + nw : t;
;         const int iv0 = ivq0, iv1 = ivq1;
;         const float gv0 = gvq0, gv1 = gvq1;
;         f32x2 x2[16], f2[16];
;         {
; #pragma unroll
;             for (int j = 0; j < 4; ++j) { const u32x4 xa = xq[j];
;                 x2[4 * j] = (f32x2){bflo(xa.x), bfhi(xa.x)}; x2[4 * j + 1] = (f32x2){bflo(xa.y), bfhi(xa.y)}; x2[4 * j + 2] = (f32x2){bflo(xa.z), bfhi(xa.z)}; x2[4 * j + 3] = (f32x2){bflo(xa.w), bfhi(xa.w)}; }
;         }
; #pragma unroll
;         for (int i = 0; i < 16; ++i) f2[i] = (f32x2){0.f, 0.f};
; #pragma unroll 1
;         for (int bt = 0; bt < 8; ++bt) {
;             if (bt < 7) { const int nb = bt + 1; const int isrc = (nb < 4) ? iv0 : iv1; const int lb = (nb & 3) * 16; PEER_LOADREC_FROM(isrc, lb); }
;             else PEER_LOADREC_MEM(eidx + (size_t)tn * 128);
;             const int myidx = __shfl((bt < 4) ? iv0 : iv1, (bt & 3) * 16 + esel16);
;             const float gsc = __shfl((bt < 4) ? gv0 : gv1, (bt & 3) * 16 + esel16) * SV[myidx], usc = SU[myidx];
;             float d[8];
; #pragma unroll
;             for (int q = 0; q < 8; ++q) d[q] = dotU(ucur[q], x2);
.LBB0_34:
	s_mov_b32 s20, s10
	s_add_i32 s10, s10, s90
	s_cmpk_gt_i32 s10, 0x7fff
	s_cselect_b64 s[18:19], -1, 0
	s_cmp_lt_i32 s10, 0x8000
	s_cselect_b32 s22, s10, s20
	s_ashr_i32 s23, s22, 31
	s_lshl_b64 s[0:1], s[22:23], 9
	s_add_u32 s24, s92, s0
	v_mov_b32_e32 v160, 0
	s_waitcnt vmcnt(8)
	v_readlane_b32 s44, v250, 42
	v_and_b32_e32 v80, 31, v96
	v_lshlrev_b32_e32 v80, 6, v80
	v_add_u32_e32 v80, s44, v80
	ds_write_b128 v80, v[76:79]
	ds_write_b128 v80, v[68:71] offset:16
	ds_write_b128 v80, v[72:75] offset:32
	ds_write_b128 v80, v[64:67] offset:48
	v_lshlrev_b32_e32 v112, 16, v76
	v_and_b32_e32 v113, 0xffff0000, v76
	v_lshlrev_b32_e32 v114, 16, v72
	v_and_b32_e32 v115, 0xffff0000, v72
	v_lshlrev_b32_e32 v116, 16, v77
	v_and_b32_e32 v117, 0xffff0000, v77
	v_lshlrev_b32_e32 v118, 16, v73
	v_and_b32_e32 v119, 0xffff0000, v73
	v_lshlrev_b32_e32 v120, 16, v78
	v_and_b32_e32 v121, 0xffff0000, v78
	v_lshlrev_b32_e32 v122, 16, v74
	v_and_b32_e32 v123, 0xffff0000, v74
	v_lshlrev_b32_e32 v124, 16, v79
	v_and_b32_e32 v125, 0xffff0000, v79
	v_lshlrev_b32_e32 v126, 16, v75
	v_and_b32_e32 v127, 0xffff0000, v75
	v_lshlrev_b32_e32 v142, 16, v68
	v_and_b32_e32 v143, 0xffff0000, v68
	v_lshlrev_b32_e32 v144, 16, v64
	v_and_b32_e32 v145, 0xffff0000, v64
	v_lshlrev_b32_e32 v146, 16, v69
	v_and_b32_e32 v147, 0xffff0000, v69
	v_lshlrev_b32_e32 v148, 16, v65
	v_and_b32_e32 v149, 0xffff0000, v65
	v_lshlrev_b32_e32 v150, 16, v70
	v_and_b32_e32 v151, 0xffff0000, v70
	v_lshlrev_b32_e32 v152, 16, v66
	v_and_b32_e32 v153, 0xffff0000, v66
	v_lshlrev_b32_e32 v154, 16, v71
	v_and_b32_e32 v155, 0xffff0000, v71
	v_lshlrev_b32_e32 v156, 16, v67
	v_and_b32_e32 v157, 0xffff0000, v67
	s_addc_u32 s25, s93, s1
	s_mov_b32 s21, 0
	s_mov_b32 s11, 0
	v_mov_b32_e32 v161, v160
	v_mov_b32_e32 v188, v160
	v_mov_b32_e32 v189, v160
	v_mov_b32_e32 v164, v160
	v_mov_b32_e32 v165, v160
	v_mov_b32_e32 v168, v160
	v_mov_b32_e32 v169, v160
	v_mov_b32_e32 v172, v160
	v_mov_b32_e32 v173, v160
	v_mov_b32_e32 v176, v160
	v_mov_b32_e32 v177, v160
	v_mov_b32_e32 v180, v160
	v_mov_b32_e32 v181, v160
	v_mov_b32_e32 v184, v160
	v_mov_b32_e32 v185, v160
	v_mov_b32_e32 v186, v160
	v_mov_b32_e32 v187, v160
	v_mov_b32_e32 v158, v160
	v_mov_b32_e32 v159, v160
	v_mov_b32_e32 v162, v160
	v_mov_b32_e32 v163, v160
	v_mov_b32_e32 v166, v160
	v_mov_b32_e32 v167, v160
	v_mov_b32_e32 v170, v160
	v_mov_b32_e32 v171, v160
	v_mov_b32_e32 v174, v160
	v_mov_b32_e32 v175, v160
	v_mov_b32_e32 v178, v160
	v_mov_b32_e32 v179, v160
	v_mov_b32_e32 v182, v160
	v_mov_b32_e32 v183, v160
	s_branch .LBB0_36
.LBB0_35:
	s_cmp_lt_u32 s11, 4
	s_cselect_b64 vcc, -1, 0
	v_or_b32_e32 v83, s60, v128
	s_waitcnt vmcnt(6)
	v_cndmask_b32_e32 v82, v225, v218, vcc
	v_lshlrev_b32_e32 v228, 2, v83
	ds_bpermute_b32 v90, v228, v82
	s_waitcnt lgkmcnt(0)
	v_ashrrev_i32_e32 v91, 31, v90
	v_lshlrev_b64 v[90:91], 2, v[90:91]
	v_lshl_add_u64 v[92:93], s[96:97], 0, v[90:91]
	v_lshl_add_u64 v[90:91], s[94:95], 0, v[90:91]
	global_load_dword v92, v[92:93], off
	s_nop 0
	global_load_dword v93, v[90:91], off
	s_mov_b32 m0, s32
	s_lshl_b32 s44, s28, 10
	s_add_u32 s44, s12, s44
	s_addc_u32 s45, s13, 0
	global_load_lds_dwordx4 v232, s[44:45] sc1
	s_add_i32 m0, s32, 0x410
	s_lshl_b32 s44, s26, 10
	s_add_u32 s44, s12, s44
	s_addc_u32 s45, s13, 0
	global_load_lds_dwordx4 v232, s[44:45] sc1
	s_add_i32 m0, s32, 0x820
	s_lshl_b32 s44, s30, 10
	s_add_u32 s44, s12, s44
	s_addc_u32 s45, s13, 0
	global_load_lds_dwordx4 v232, s[44:45] sc1
	s_add_i32 m0, s32, 0xc30
	s_lshl_b32 s44, s40, 10
	s_add_u32 s44, s12, s44
	s_addc_u32 s45, s13, 0
	global_load_lds_dwordx4 v232, s[44:45] sc1
	s_add_i32 m0, s32, 0x1040
	s_lshl_b32 s44, s34, 10
	s_add_u32 s44, s12, s44
	s_addc_u32 s45, s13, 0
	global_load_lds_dwordx4 v232, s[44:45] sc1
	s_add_i32 m0, s32, 0x1450
	s_lshl_b32 s44, s38, 10
	s_add_u32 s44, s12, s44
	s_addc_u32 s45, s13, 0
	global_load_lds_dwordx4 v232, s[44:45] sc1
	s_add_i32 m0, s32, 0x1860
	s_lshl_b32 s44, s50, 10
	s_add_u32 s44, s12, s44
	s_addc_u32 s45, s13, 0
	global_load_lds_dwordx4 v232, s[44:45] sc1
	s_add_i32 m0, s32, 0x1c70
	s_lshl_b32 s44, s48, 10
	s_add_u32 s44, s12, s44
	s_addc_u32 s45, s13, 0
	global_load_lds_dwordx4 v232, s[44:45] sc1
	s_add_i32 m0, s32, 0x2080
	s_lshl_b32 s44, s54, 10
	s_add_u32 s44, s12, s44
	s_addc_u32 s45, s13, 0
	global_load_lds_dwordx4 v232, s[44:45] sc1
	s_add_i32 m0, s32, 0x2490
	s_lshl_b32 s44, s46, 10
	s_add_u32 s44, s12, s44
	s_addc_u32 s45, s13, 0
	global_load_lds_dwordx4 v232, s[44:45] sc1
	s_add_i32 m0, s32, 0x28a0
	s_lshl_b32 s44, s58, 10
	s_add_u32 s44, s12, s44
	s_addc_u32 s45, s13, 0
	global_load_lds_dwordx4 v232, s[44:45] sc1
	s_add_i32 m0, s32, 0x2cb0
	s_lshl_b32 s44, s36, 10
	s_add_u32 s44, s12, s44
	s_addc_u32 s45, s13, 0
	global_load_lds_dwordx4 v232, s[44:45] sc1
	s_add_i32 m0, s32, 0x30c0
	s_lshl_b32 s44, s62, 10
	s_add_u32 s44, s12, s44
	s_addc_u32 s45, s13, 0
	global_load_lds_dwordx4 v232, s[44:45] sc1
	s_add_i32 m0, s32, 0x34d0
	s_lshl_b32 s44, s52, 10
	s_add_u32 s44, s12, s44
	s_addc_u32 s45, s13, 0
	global_load_lds_dwordx4 v232, s[44:45] sc1
	s_add_i32 m0, s32, 0x38e0
	s_lshl_b32 s44, s64, 10
	s_add_u32 s44, s12, s44
	s_addc_u32 s45, s13, 0
	global_load_lds_dwordx4 v232, s[44:45] sc1
	s_add_i32 m0, s32, 0x3cf0
	s_lshl_b32 s44, s56, 10
	s_add_u32 s44, s12, s44
	s_addc_u32 s45, s13, 0
	global_load_lds_dwordx4 v232, s[44:45] sc1
	ds_read_b128 v[64:67], v210
	ds_read_b128 v[68:71], v210 offset:16
	ds_read_b128 v[72:75], v210 offset:32
	ds_read_b128 v[76:79], v210 offset:48
	v_cvt_scalef32_pk_bf16_fp4 v84, v60, 1.0
	v_cvt_scalef32_pk_bf16_fp4 v85, v60, 1.0 op_sel:[1,0,0]
	v_cvt_scalef32_pk_bf16_fp4 v86, v60, 1.0 op_sel:[0,1,0]
	v_cvt_scalef32_pk_bf16_fp4 v87, v60, 1.0 op_sel:[1,1,0]
	v_cvt_scalef32_pk_bf16_fp4 v88, v61, 1.0
	v_cvt_scalef32_pk_bf16_fp4 v89, v61, 1.0 op_sel:[1,0,0]
	v_cvt_scalef32_pk_bf16_fp4 v90, v61, 1.0 op_sel:[0,1,0]
	v_cvt_scalef32_pk_bf16_fp4 v91, v61, 1.0 op_sel:[1,1,0]
	s_waitcnt lgkmcnt(3)
; DI float dotU(const URow& q, const f32x2 (&x2)[16]) { return dot32r(dec6(q), x2); }
; DI float dotU(const URow& q, const f32x2 (&x2)[16]) {
;     f32x2 a0 = {0.f, 0.f}, a1 = {0.f, 0.f};
; #pragma unroll
;     for (int d = 0; d < 4; ++d) {
;         a0 += __builtin_amdgcn_cvt_scalef32_pk_f32_fp4(q[d], 1.0f, 0) * x2[4 * d];     a1 += __builtin_amdgcn_cvt_scalef32_pk_f32_fp4(q[d], 1.0f, 1) * x2[4 * d + 1];
;         a0 += __builtin_amdgcn_cvt_scalef32_pk_f32_fp4(q[d], 1.0f, 2) * x2[4 * d + 2]; a1 += __builtin_amdgcn_cvt_scalef32_pk_f32_fp4(q[d], 1.0f, 3) * x2[4 * d + 3];
;     }
;     a0 += a1;
;     return a0.x + a0.y;
; }
; DI void peer_phase(const Params& p, int layer, bool dry) {
;     ...
;             const int myidx = __shfl((bt < 4) ? iv0 : iv1, (bt & 3) * 16 + esel16);
;             const float gsc = __shfl((bt < 4) ? gv0 : gv1, (bt & 3) * 16 + esel16) * SV[myidx], usc = SU[myidx];
;             float d[8];
; #pragma unroll
;             for (int q = 0; q < 8; ++q) d[q] = dotU(ucur[q], x2);
;             float r4[4], r2[2], r1;
; #pragma unroll
;             for (int j = 0; j < 4; ++j) { const float send = b4 ? d[j] : d[j + 4], keep = b4 ? d[j + 4] : d[j]; r4[j] = keep + __shfl_xor(send, 16); }
; #pragma unroll
;             for (int j = 0; j < 2; ++j) { const float send = b3 ? r4[j] : r4[j + 2], keep = b3 ? r4[j + 2] : r4[j]; r2[j] = keep + __shfl_xor(send, 8); }
;             { const float send = b2_ ? r2[0] : r2[1], keep = b2_ ? r2[1] : r2[0]; r1 = keep + __shfl_xor(send, 4); }
;             r1 += __shfl_xor(r1, 2); r1 += __shfl_xor(r1, 1);
	v_mfma_f32_16x16x32_bf16 v[80:83], v[64:67], v[84:87], 0
	ds_read_b128 v[64:67], v210 offset:256
	v_cvt_scalef32_pk_bf16_fp4 v84, v62, 1.0
	v_cvt_scalef32_pk_bf16_fp4 v85, v62, 1.0 op_sel:[1,0,0]
	v_cvt_scalef32_pk_bf16_fp4 v86, v62, 1.0 op_sel:[0,1,0]
	v_cvt_scalef32_pk_bf16_fp4 v87, v62, 1.0 op_sel:[1,1,0]
	s_waitcnt lgkmcnt(3)
	v_mfma_f32_16x16x32_bf16 v[80:83], v[68:71], v[88:91], v[80:83]
	ds_read_b128 v[68:71], v210 offset:272
	v_cvt_scalef32_pk_bf16_fp4 v88, v63, 1.0
	v_cvt_scalef32_pk_bf16_fp4 v89, v63, 1.0 op_sel:[1,0,0]
	v_cvt_scalef32_pk_bf16_fp4 v90, v63, 1.0 op_sel:[0,1,0]
	v_cvt_scalef32_pk_bf16_fp4 v91, v63, 1.0 op_sel:[1,1,0]
	s_waitcnt lgkmcnt(3)
	v_mfma_f32_16x16x32_bf16 v[80:83], v[72:75], v[84:87], v[80:83]
	ds_read_b128 v[72:75], v210 offset:288
	v_cvt_scalef32_pk_bf16_fp4 v84, v56, 1.0
	v_cvt_scalef32_pk_bf16_fp4 v85, v56, 1.0 op_sel:[1,0,0]
	v_cvt_scalef32_pk_bf16_fp4 v86, v56, 1.0 op_sel:[0,1,0]
	v_cvt_scalef32_pk_bf16_fp4 v87, v56, 1.0 op_sel:[1,1,0]
	s_waitcnt lgkmcnt(3)
	v_mfma_f32_16x16x32_bf16 v[80:83], v[76:79], v[88:91], v[80:83]
	ds_read_b128 v[76:79], v210 offset:304
	v_cvt_scalef32_pk_bf16_fp4 v88, v57, 1.0
	v_cvt_scalef32_pk_bf16_fp4 v89, v57, 1.0 op_sel:[1,0,0]
	v_cvt_scalef32_pk_bf16_fp4 v90, v57, 1.0 op_sel:[0,1,0]
	v_cvt_scalef32_pk_bf16_fp4 v91, v57, 1.0 op_sel:[1,1,0]
	s_waitcnt lgkmcnt(3)
	v_mfma_f32_16x16x32_bf16 v[80:83], v[64:67], v[84:87], v[80:83]
	ds_read_b128 v[64:67], v210 offset:512
	v_cvt_scalef32_pk_bf16_fp4 v84, v58, 1.0
	v_cvt_scalef32_pk_bf16_fp4 v85, v58, 1.0 op_sel:[1,0,0]
	v_cvt_scalef32_pk_bf16_fp4 v86, v58, 1.0 op_sel:[0,1,0]
	v_cvt_scalef32_pk_bf16_fp4 v87, v58, 1.0 op_sel:[1,1,0]
	s_waitcnt lgkmcnt(3)
	v_mfma_f32_16x16x32_bf16 v[80:83], v[68:71], v[88:91], v[80:83]
	ds_read_b128 v[68:71], v210 offset:528
	v_cvt_scalef32_pk_bf16_fp4 v88, v59, 1.0
	v_cvt_scalef32_pk_bf16_fp4 v89, v59, 1.0 op_sel:[1,0,0]
	v_cvt_scalef32_pk_bf16_fp4 v90, v59, 1.0 op_sel:[0,1,0]
	v_cvt_scalef32_pk_bf16_fp4 v91, v59, 1.0 op_sel:[1,1,0]
	s_waitcnt lgkmcnt(3)
	v_mfma_f32_16x16x32_bf16 v[80:83], v[72:75], v[84:87], v[80:83]
	ds_read_b128 v[72:75], v210 offset:544
	v_cvt_scalef32_pk_bf16_fp4 v84, v52, 1.0
	v_cvt_scalef32_pk_bf16_fp4 v85, v52, 1.0 op_sel:[1,0,0]
	v_cvt_scalef32_pk_bf16_fp4 v86, v52, 1.0 op_sel:[0,1,0]
	v_cvt_scalef32_pk_bf16_fp4 v87, v52, 1.0 op_sel:[1,1,0]
	s_waitcnt lgkmcnt(3)
	v_mfma_f32_16x16x32_bf16 v[80:83], v[76:79], v[88:91], v[80:83]
	ds_read_b128 v[76:79], v210 offset:560
	v_cvt_scalef32_pk_bf16_fp4 v88, v53, 1.0
	v_cvt_scalef32_pk_bf16_fp4 v89, v53, 1.0 op_sel:[1,0,0]
	v_cvt_scalef32_pk_bf16_fp4 v90, v53, 1.0 op_sel:[0,1,0]
	v_cvt_scalef32_pk_bf16_fp4 v91, v53, 1.0 op_sel:[1,1,0]
	s_waitcnt lgkmcnt(3)
	v_mfma_f32_16x16x32_bf16 v[80:83], v[64:67], v[84:87], v[80:83]
	ds_read_b128 v[64:67], v210 offset:768
	v_cvt_scalef32_pk_bf16_fp4 v84, v54, 1.0
	v_cvt_scalef32_pk_bf16_fp4 v85, v54, 1.0 op_sel:[1,0,0]
	v_cvt_scalef32_pk_bf16_fp4 v86, v54, 1.0 op_sel:[0,1,0]
	v_cvt_scalef32_pk_bf16_fp4 v87, v54, 1.0 op_sel:[1,1,0]
	s_waitcnt lgkmcnt(3)
	v_mfma_f32_16x16x32_bf16 v[80:83], v[68:71], v[88:91], v[80:83]
	ds_read_b128 v[68:71], v210 offset:784
	v_cvt_scalef32_pk_bf16_fp4 v88, v55, 1.0
	v_cvt_scalef32_pk_bf16_fp4 v89, v55, 1.0 op_sel:[1,0,0]
	v_cvt_scalef32_pk_bf16_fp4 v90, v55, 1.0 op_sel:[0,1,0]
	v_cvt_scalef32_pk_bf16_fp4 v91, v55, 1.0 op_sel:[1,1,0]
	s_waitcnt lgkmcnt(3)
	v_mfma_f32_16x16x32_bf16 v[80:83], v[72:75], v[84:87], v[80:83]
	ds_read_b128 v[72:75], v210 offset:800
	v_cvt_scalef32_pk_bf16_fp4 v84, v48, 1.0
	v_cvt_scalef32_pk_bf16_fp4 v85, v48, 1.0 op_sel:[1,0,0]
	v_cvt_scalef32_pk_bf16_fp4 v86, v48, 1.0 op_sel:[0,1,0]
	v_cvt_scalef32_pk_bf16_fp4 v87, v48, 1.0 op_sel:[1,1,0]
	s_waitcnt lgkmcnt(3)
	v_mfma_f32_16x16x32_bf16 v[80:83], v[76:79], v[88:91], v[80:83]
	ds_read_b128 v[76:79], v210 offset:816
	v_cvt_scalef32_pk_bf16_fp4 v88, v49, 1.0
	v_cvt_scalef32_pk_bf16_fp4 v89, v49, 1.0 op_sel:[1,0,0]
	v_cvt_scalef32_pk_bf16_fp4 v90, v49, 1.0 op_sel:[0,1,0]
	v_cvt_scalef32_pk_bf16_fp4 v91, v49, 1.0 op_sel:[1,1,0]
	s_waitcnt lgkmcnt(3)
	v_mfma_f32_16x16x32_bf16 v[80:83], v[64:67], v[84:87], v[80:83]
	ds_read_b128 v[64:67], v210 offset:1024
	v_cvt_scalef32_pk_bf16_fp4 v84, v50, 1.0
	v_cvt_scalef32_pk_bf16_fp4 v85, v50, 1.0 op_sel:[1,0,0]
	v_cvt_scalef32_pk_bf16_fp4 v86, v50, 1.0 op_sel:[0,1,0]
	v_cvt_scalef32_pk_bf16_fp4 v87, v50, 1.0 op_sel:[1,1,0]
	s_waitcnt lgkmcnt(3)
	v_mfma_f32_16x16x32_bf16 v[80:83], v[68:71], v[88:91], v[80:83]
	ds_read_b128 v[68:71], v210 offset:1040
	v_cvt_scalef32_pk_bf16_fp4 v88, v51, 1.0
	v_cvt_scalef32_pk_bf16_fp4 v89, v51, 1.0 op_sel:[1,0,0]
	v_cvt_scalef32_pk_bf16_fp4 v90, v51, 1.0 op_sel:[0,1,0]
	v_cvt_scalef32_pk_bf16_fp4 v91, v51, 1.0 op_sel:[1,1,0]
	s_waitcnt lgkmcnt(3)
	v_mfma_f32_16x16x32_bf16 v[80:83], v[72:75], v[84:87], v[80:83]
	ds_read_b128 v[72:75], v210 offset:1056
	v_cvt_scalef32_pk_bf16_fp4 v84, v44, 1.0
	v_cvt_scalef32_pk_bf16_fp4 v85, v44, 1.0 op_sel:[1,0,0]
	v_cvt_scalef32_pk_bf16_fp4 v86, v44, 1.0 op_sel:[0,1,0]
	v_cvt_scalef32_pk_bf16_fp4 v87, v44, 1.0 op_sel:[1,1,0]
	s_waitcnt lgkmcnt(3)
	v_mfma_f32_16x16x32_bf16 v[80:83], v[76:79], v[88:91], v[80:83]
	ds_read_b128 v[76:79], v210 offset:1072
	v_cvt_scalef32_pk_bf16_fp4 v88, v45, 1.0
	v_cvt_scalef32_pk_bf16_fp4 v89, v45, 1.0 op_sel:[1,0,0]
	v_cvt_scalef32_pk_bf16_fp4 v90, v45, 1.0 op_sel:[0,1,0]
	v_cvt_scalef32_pk_bf16_fp4 v91, v45, 1.0 op_sel:[1,1,0]
	s_waitcnt lgkmcnt(3)
	v_mfma_f32_16x16x32_bf16 v[80:83], v[64:67], v[84:87], v[80:83]
	ds_read_b128 v[64:67], v210 offset:1280
	v_cvt_scalef32_pk_bf16_fp4 v84, v46, 1.0
	v_cvt_scalef32_pk_bf16_fp4 v85, v46, 1.0 op_sel:[1,0,0]
	v_cvt_scalef32_pk_bf16_fp4 v86, v46, 1.0 op_sel:[0,1,0]
	v_cvt_scalef32_pk_bf16_fp4 v87, v46, 1.0 op_sel:[1,1,0]
	s_waitcnt lgkmcnt(3)
; DI float dotU(const URow& q, const f32x2 (&x2)[16]) { return dot32r(dec6(q), x2); }
; DI void axpyV(f32x2 (&f2)[16], float a, const VRow& q) { axpy32r(f2, a, dec6(q)); }
; DI float gelu_tanh(float x) {
;     const float u = 0.7978845608f * (x + 0.044715f * x * x * x);
;     const float th = 1.f - 2.f / (__expf(2.f * u) + 1.f);
;     return 0.5f * x * (1.f + th);
; }
; DI void peer_phase(const Params& p, int layer, bool dry) {
;     ...
;             float d[8];
; #pragma unroll
;             for (int q = 0; q < 8; ++q) d[q] = dotU(ucur[q], x2);
;             float r4[4], r2[2], r1;
; #pragma unroll
;             for (int j = 0; j < 4; ++j) { const float send = b4 ? d[j] : d[j + 4], keep = b4 ? d[j + 4] : d[j]; r4[j] = keep + __shfl_xor(send, 16); }
; #pragma unroll
;             for (int j = 0; j < 2; ++j) { const float send = b3 ? r4[j] : r4[j + 2], keep = b3 ? r4[j + 2] : r4[j]; r2[j] = keep + __shfl_xor(send, 8); }
;             { const float send = b2_ ? r2[0] : r2[1], keep = b2_ ? r2[1] : r2[0]; r1 = keep + __shfl_xor(send, 4); }
;             r1 += __shfl_xor(r1, 2); r1 += __shfl_xor(r1, 1);
;             const float act = gelu_tanh(r1 * usc) * gsc;
; #pragma unroll
;             for (int q = 0; q < 8; ++q) { const float a = __shfl(act, (lane & 32) | ((q >> 2) << 4) | (((q >> 1) & 1) << 3) | ((q & 1) << 2)); axpyV(f2, a, vcur[q]); }
	v_mfma_f32_16x16x32_bf16 v[80:83], v[68:71], v[88:91], v[80:83]
	ds_read_b128 v[68:71], v210 offset:1296
	v_cvt_scalef32_pk_bf16_fp4 v88, v47, 1.0
	v_cvt_scalef32_pk_bf16_fp4 v89, v47, 1.0 op_sel:[1,0,0]
	v_cvt_scalef32_pk_bf16_fp4 v90, v47, 1.0 op_sel:[0,1,0]
	v_cvt_scalef32_pk_bf16_fp4 v91, v47, 1.0 op_sel:[1,1,0]
	s_waitcnt lgkmcnt(3)
	v_mfma_f32_16x16x32_bf16 v[80:83], v[72:75], v[84:87], v[80:83]
	ds_read_b128 v[72:75], v210 offset:1312
	v_cvt_scalef32_pk_bf16_fp4 v84, v40, 1.0
	v_cvt_scalef32_pk_bf16_fp4 v85, v40, 1.0 op_sel:[1,0,0]
	v_cvt_scalef32_pk_bf16_fp4 v86, v40, 1.0 op_sel:[0,1,0]
	v_cvt_scalef32_pk_bf16_fp4 v87, v40, 1.0 op_sel:[1,1,0]
	s_waitcnt lgkmcnt(3)
	v_mfma_f32_16x16x32_bf16 v[80:83], v[76:79], v[88:91], v[80:83]
	ds_read_b128 v[76:79], v210 offset:1328
	v_cvt_scalef32_pk_bf16_fp4 v88, v41, 1.0
	v_cvt_scalef32_pk_bf16_fp4 v89, v41, 1.0 op_sel:[1,0,0]
	v_cvt_scalef32_pk_bf16_fp4 v90, v41, 1.0 op_sel:[0,1,0]
	v_cvt_scalef32_pk_bf16_fp4 v91, v41, 1.0 op_sel:[1,1,0]
	s_waitcnt lgkmcnt(3)
	v_mfma_f32_16x16x32_bf16 v[80:83], v[64:67], v[84:87], v[80:83]
	ds_read_b128 v[64:67], v210 offset:1536
	v_cvt_scalef32_pk_bf16_fp4 v84, v42, 1.0
	v_cvt_scalef32_pk_bf16_fp4 v85, v42, 1.0 op_sel:[1,0,0]
	v_cvt_scalef32_pk_bf16_fp4 v86, v42, 1.0 op_sel:[0,1,0]
	v_cvt_scalef32_pk_bf16_fp4 v87, v42, 1.0 op_sel:[1,1,0]
	s_waitcnt lgkmcnt(3)
	v_mfma_f32_16x16x32_bf16 v[80:83], v[68:71], v[88:91], v[80:83]
	ds_read_b128 v[68:71], v210 offset:1552
	v_cvt_scalef32_pk_bf16_fp4 v88, v43, 1.0
	v_cvt_scalef32_pk_bf16_fp4 v89, v43, 1.0 op_sel:[1,0,0]
	v_cvt_scalef32_pk_bf16_fp4 v90, v43, 1.0 op_sel:[0,1,0]
	v_cvt_scalef32_pk_bf16_fp4 v91, v43, 1.0 op_sel:[1,1,0]
	s_waitcnt lgkmcnt(3)
	v_mfma_f32_16x16x32_bf16 v[80:83], v[72:75], v[84:87], v[80:83]
	ds_read_b128 v[72:75], v210 offset:1568
	v_cvt_scalef32_pk_bf16_fp4 v84, v36, 1.0
	v_cvt_scalef32_pk_bf16_fp4 v85, v36, 1.0 op_sel:[1,0,0]
	v_cvt_scalef32_pk_bf16_fp4 v86, v36, 1.0 op_sel:[0,1,0]
	v_cvt_scalef32_pk_bf16_fp4 v87, v36, 1.0 op_sel:[1,1,0]
	s_waitcnt lgkmcnt(3)
	v_mfma_f32_16x16x32_bf16 v[80:83], v[76:79], v[88:91], v[80:83]
	ds_read_b128 v[76:79], v210 offset:1584
	v_cvt_scalef32_pk_bf16_fp4 v88, v37, 1.0
	v_cvt_scalef32_pk_bf16_fp4 v89, v37, 1.0 op_sel:[1,0,0]
	v_cvt_scalef32_pk_bf16_fp4 v90, v37, 1.0 op_sel:[0,1,0]
	v_cvt_scalef32_pk_bf16_fp4 v91, v37, 1.0 op_sel:[1,1,0]
	s_waitcnt lgkmcnt(3)
	v_mfma_f32_16x16x32_bf16 v[80:83], v[64:67], v[84:87], v[80:83]
	ds_read_b128 v[64:67], v210 offset:1792
	v_cvt_scalef32_pk_bf16_fp4 v84, v38, 1.0
	v_cvt_scalef32_pk_bf16_fp4 v85, v38, 1.0 op_sel:[1,0,0]
	v_cvt_scalef32_pk_bf16_fp4 v86, v38, 1.0 op_sel:[0,1,0]
	v_cvt_scalef32_pk_bf16_fp4 v87, v38, 1.0 op_sel:[1,1,0]
	s_waitcnt lgkmcnt(3)
	v_mfma_f32_16x16x32_bf16 v[80:83], v[68:71], v[88:91], v[80:83]
	ds_read_b128 v[68:71], v210 offset:1808
	v_cvt_scalef32_pk_bf16_fp4 v88, v39, 1.0
	v_cvt_scalef32_pk_bf16_fp4 v89, v39, 1.0 op_sel:[1,0,0]
	v_cvt_scalef32_pk_bf16_fp4 v90, v39, 1.0 op_sel:[0,1,0]
	v_cvt_scalef32_pk_bf16_fp4 v91, v39, 1.0 op_sel:[1,1,0]
	s_waitcnt lgkmcnt(3)
	v_mfma_f32_16x16x32_bf16 v[80:83], v[72:75], v[84:87], v[80:83]
	ds_read_b128 v[72:75], v210 offset:1824
	v_cvt_scalef32_pk_bf16_fp4 v84, v32, 1.0
	v_cvt_scalef32_pk_bf16_fp4 v85, v32, 1.0 op_sel:[1,0,0]
	v_cvt_scalef32_pk_bf16_fp4 v86, v32, 1.0 op_sel:[0,1,0]
	v_cvt_scalef32_pk_bf16_fp4 v87, v32, 1.0 op_sel:[1,1,0]
	s_waitcnt lgkmcnt(3)
	v_mfma_f32_16x16x32_bf16 v[80:83], v[76:79], v[88:91], v[80:83]
	ds_read_b128 v[76:79], v210 offset:1840
	v_cvt_scalef32_pk_bf16_fp4 v88, v33, 1.0
	v_cvt_scalef32_pk_bf16_fp4 v89, v33, 1.0 op_sel:[1,0,0]
	v_cvt_scalef32_pk_bf16_fp4 v90, v33, 1.0 op_sel:[0,1,0]
	v_cvt_scalef32_pk_bf16_fp4 v91, v33, 1.0 op_sel:[1,1,0]
	s_waitcnt lgkmcnt(3)
	v_mfma_f32_16x16x32_bf16 v[80:83], v[64:67], v[84:87], v[80:83]
	v_cvt_scalef32_pk_bf16_fp4 v84, v34, 1.0
	v_cvt_scalef32_pk_bf16_fp4 v85, v34, 1.0 op_sel:[1,0,0]
	v_cvt_scalef32_pk_bf16_fp4 v86, v34, 1.0 op_sel:[0,1,0]
	v_cvt_scalef32_pk_bf16_fp4 v87, v34, 1.0 op_sel:[1,1,0]
	s_waitcnt lgkmcnt(2)
	v_mfma_f32_16x16x32_bf16 v[80:83], v[68:71], v[88:91], v[80:83]
	v_cvt_scalef32_pk_bf16_fp4 v88, v35, 1.0
	v_cvt_scalef32_pk_bf16_fp4 v89, v35, 1.0 op_sel:[1,0,0]
	v_cvt_scalef32_pk_bf16_fp4 v90, v35, 1.0 op_sel:[0,1,0]
	v_cvt_scalef32_pk_bf16_fp4 v91, v35, 1.0 op_sel:[1,1,0]
	s_waitcnt lgkmcnt(1)
	v_mfma_f32_16x16x32_bf16 v[80:83], v[72:75], v[84:87], v[80:83]
	s_waitcnt lgkmcnt(0)
	v_mfma_f32_16x16x32_bf16 v[80:83], v[76:79], v[88:91], v[80:83]
	s_waitcnt vmcnt(22)
	v_cndmask_b32_e32 v54, v227, v226, vcc
	ds_bpermute_b32 v54, v228, v54
	v_cvt_scalef32_pk_f32_fp4 v[230:231], v28, 1.0
	s_nop 7
	s_waitcnt lgkmcnt(0)
	s_waitcnt vmcnt(16)
	v_mul_f32_e32 v55, v93, v80
	v_mul_f32_e32 v46, 0x3d372713, v55
	v_mul_f32_e32 v46, v55, v46
	v_fma_f32 v46, v55, v46, v55
	v_mul_f32_e32 v46, 0x3f4c422a, v46
	v_add_f32_e32 v46, v46, v46
	v_mul_f32_e32 v46, 0x3fb8aa3b, v46
	v_exp_f32_e32 v52, v46
	s_nop 0
	v_add_f32_e32 v93, 1.0, v52
	v_div_scale_f32 v94, s[28:29], v93, v93, 2.0
	v_rcp_f32_e32 v95, v94
	s_add_i32 s11, s11, 1
	s_cmpk_eq_i32 s21, 0x80
	v_fma_f32 v190, -v94, v95, 1.0
	v_fmac_f32_e32 v95, v190, v95
	v_div_scale_f32 v190, vcc, 2.0, v93, 2.0
	v_mul_f32_e32 v191, v190, v95
	v_fma_f32 v228, -v94, v191, v190
	v_fmac_f32_e32 v191, v228, v95
	v_fma_f32 v94, -v94, v191, v190
	v_div_fmas_f32 v94, v94, v95, v191
	v_div_fixup_f32 v93, v94, v93, 2.0
	v_sub_f32_e32 v94, 1.0, v93
	v_mul_f32_e32 v93, 0.5, v55
	v_add_f32_e32 v55, 1.0, v94
	v_pk_mul_f32 v[54:55], v[92:93], v[54:55]
	v_pk_mul_f32 v[190:191], v[54:55], v[54:55] op_sel:[0,1] op_sel_hi:[1,0]
	ds_bpermute_b32 v228, v216, v190
	s_waitcnt lgkmcnt(0)
; DI void axpyV(f32x2 (&f2)[16], float a, const VRow& q) { axpy32r(f2, a, dec6(q)); }
; #define PEER_SWAP() do { _Pragma("unroll") for (int q_ = 0; q_ < 8; ++q_) _Pragma("unroll") for (int c_ = 0; c_ < 4; ++c_) { \
;             const auto r_ = __builtin_amdgcn_permlane32_swap(ra[q_][c_], rb[q_][c_], false, false); ucur[q_][c_] = r_[0]; vcur[q_][c_] = r_[1]; } } while (0)
; DI void axpyV(f32x2 (&f2)[16], float a, const VRow& q) {
;     const f32x2 aa = {a, a};
; #pragma unroll
;     for (int d = 0; d < 4; ++d) {
;         f2[4 * d] += aa * __builtin_amdgcn_cvt_scalef32_pk_f32_fp4(q[d], 1.0f, 0);     f2[4 * d + 1] += aa * __builtin_amdgcn_cvt_scalef32_pk_f32_fp4(q[d], 1.0f, 1);
;         f2[4 * d + 2] += aa * __builtin_amdgcn_cvt_scalef32_pk_f32_fp4(q[d], 1.0f, 2); f2[4 * d + 3] += aa * __builtin_amdgcn_cvt_scalef32_pk_f32_fp4(q[d], 1.0f, 3);
;     }
; }
; DI void peer_phase(const Params& p, int layer, bool dry) {
;     ...
;             const float act = gelu_tanh(r1 * usc) * gsc;
; #pragma unroll
;             for (int q = 0; q < 8; ++q) { const float a = __shfl(act, (lane & 32) | ((q >> 2) << 4) | (((q >> 1) & 1) << 3) | ((q & 1) << 2)); axpyV(f2, a, vcur[q]); }
;             PEER_SWAP();
	v_pk_fma_f32 v[188:189], v[230:231], v[228:229], v[188:189] op_sel_hi:[1,0,1]
	v_cvt_scalef32_pk_f32_fp4 v[230:231], v28, 1.0 op_sel:[1,0,0]
	v_pk_fma_f32 v[164:165], v[228:229], v[230:231], v[164:165] op_sel_hi:[0,1,1]
	v_cvt_scalef32_pk_f32_fp4 v[230:231], v28, 1.0 op_sel:[0,1,0]
	v_pk_fma_f32 v[168:169], v[228:229], v[230:231], v[168:169] op_sel_hi:[0,1,1]
	v_cvt_scalef32_pk_f32_fp4 v[230:231], v28, 1.0 op_sel:[1,1,0]
	v_pk_fma_f32 v[172:173], v[228:229], v[230:231], v[172:173] op_sel_hi:[0,1,1]
	v_cvt_scalef32_pk_f32_fp4 v[230:231], v29, 1.0
	v_pk_fma_f32 v[176:177], v[228:229], v[230:231], v[176:177] op_sel_hi:[0,1,1]
	v_cvt_scalef32_pk_f32_fp4 v[230:231], v29, 1.0 op_sel:[1,0,0]
	v_pk_fma_f32 v[180:181], v[228:229], v[230:231], v[180:181] op_sel_hi:[0,1,1]
	v_cvt_scalef32_pk_f32_fp4 v[230:231], v29, 1.0 op_sel:[0,1,0]
	v_cvt_scalef32_pk_f32_fp4 v[28:29], v29, 1.0 op_sel:[1,1,0]
	v_pk_fma_f32 v[28:29], v[228:229], v[28:29], v[186:187] op_sel_hi:[0,1,1]
	v_cvt_scalef32_pk_f32_fp4 v[186:187], v30, 1.0
	v_pk_fma_f32 v[158:159], v[228:229], v[186:187], v[158:159] op_sel_hi:[0,1,1]
	v_cvt_scalef32_pk_f32_fp4 v[186:187], v30, 1.0 op_sel:[1,0,0]
	v_pk_fma_f32 v[162:163], v[228:229], v[186:187], v[162:163] op_sel_hi:[0,1,1]
	v_cvt_scalef32_pk_f32_fp4 v[186:187], v30, 1.0 op_sel:[0,1,0]
	v_pk_fma_f32 v[166:167], v[228:229], v[186:187], v[166:167] op_sel_hi:[0,1,1]
	v_cvt_scalef32_pk_f32_fp4 v[186:187], v30, 1.0 op_sel:[1,1,0]
	v_pk_fma_f32 v[170:171], v[228:229], v[186:187], v[170:171] op_sel_hi:[0,1,1]
	v_cvt_scalef32_pk_f32_fp4 v[186:187], v31, 1.0
	ds_bpermute_b32 v30, v217, v190
	v_pk_fma_f32 v[174:175], v[228:229], v[186:187], v[174:175] op_sel_hi:[0,1,1]
	v_cvt_scalef32_pk_f32_fp4 v[186:187], v31, 1.0 op_sel:[1,0,0]
	v_pk_fma_f32 v[178:179], v[228:229], v[186:187], v[178:179] op_sel_hi:[0,1,1]
	v_cvt_scalef32_pk_f32_fp4 v[186:187], v31, 1.0 op_sel:[0,1,0]
	v_pk_fma_f32 v[182:183], v[228:229], v[186:187], v[182:183] op_sel_hi:[0,1,1]
	v_cvt_scalef32_pk_f32_fp4 v[186:187], v31, 1.0 op_sel:[1,1,0]
	v_pk_fma_f32 v[160:161], v[228:229], v[186:187], v[160:161] op_sel_hi:[0,1,1]
	v_cvt_scalef32_pk_f32_fp4 v[186:187], v24, 1.0
	s_waitcnt lgkmcnt(0)
	v_pk_fma_f32 v[186:187], v[186:187], v[30:31], v[188:189] op_sel_hi:[1,0,1]
	v_cvt_scalef32_pk_f32_fp4 v[188:189], v24, 1.0 op_sel:[1,0,0]
	v_pk_fma_f32 v[164:165], v[30:31], v[188:189], v[164:165] op_sel_hi:[0,1,1]
	v_cvt_scalef32_pk_f32_fp4 v[188:189], v24, 1.0 op_sel:[0,1,0]
	v_pk_fma_f32 v[168:169], v[30:31], v[188:189], v[168:169] op_sel_hi:[0,1,1]
	v_cvt_scalef32_pk_f32_fp4 v[188:189], v24, 1.0 op_sel:[1,1,0]
	v_pk_fma_f32 v[172:173], v[30:31], v[188:189], v[172:173] op_sel_hi:[0,1,1]
	v_cvt_scalef32_pk_f32_fp4 v[188:189], v25, 1.0
	v_pk_fma_f32 v[176:177], v[30:31], v[188:189], v[176:177] op_sel_hi:[0,1,1]
	v_cvt_scalef32_pk_f32_fp4 v[188:189], v25, 1.0 op_sel:[1,0,0]
	v_pk_fma_f32 v[180:181], v[30:31], v[188:189], v[180:181] op_sel_hi:[0,1,1]
	v_cvt_scalef32_pk_f32_fp4 v[188:189], v25, 1.0 op_sel:[0,1,0]
	v_cvt_scalef32_pk_f32_fp4 v[24:25], v25, 1.0 op_sel:[1,1,0]
	v_pk_fma_f32 v[24:25], v[30:31], v[24:25], v[28:29] op_sel_hi:[0,1,1]
	v_cvt_scalef32_pk_f32_fp4 v[28:29], v26, 1.0
	v_pk_fma_f32 v[28:29], v[30:31], v[28:29], v[158:159] op_sel_hi:[0,1,1]
	v_cvt_scalef32_pk_f32_fp4 v[158:159], v26, 1.0 op_sel:[1,0,0]
	v_pk_fma_f32 v[158:159], v[30:31], v[158:159], v[162:163] op_sel_hi:[0,1,1]
	v_cvt_scalef32_pk_f32_fp4 v[162:163], v26, 1.0 op_sel:[0,1,0]
	v_pk_fma_f32 v[162:163], v[30:31], v[162:163], v[166:167] op_sel_hi:[0,1,1]
	v_cvt_scalef32_pk_f32_fp4 v[166:167], v26, 1.0 op_sel:[1,1,0]
	v_pk_fma_f32 v[166:167], v[30:31], v[166:167], v[170:171] op_sel_hi:[0,1,1]
	v_cvt_scalef32_pk_f32_fp4 v[170:171], v27, 1.0
	ds_bpermute_b32 v26, v219, v190
	v_pk_fma_f32 v[170:171], v[30:31], v[170:171], v[174:175] op_sel_hi:[0,1,1]
	v_cvt_scalef32_pk_f32_fp4 v[174:175], v27, 1.0 op_sel:[1,0,0]
	v_pk_fma_f32 v[174:175], v[30:31], v[174:175], v[178:179] op_sel_hi:[0,1,1]
	v_cvt_scalef32_pk_f32_fp4 v[178:179], v27, 1.0 op_sel:[0,1,0]
	v_pk_fma_f32 v[184:185], v[228:229], v[230:231], v[184:185] op_sel_hi:[0,1,1]
	v_pk_fma_f32 v[178:179], v[30:31], v[178:179], v[182:183] op_sel_hi:[0,1,1]
	v_cvt_scalef32_pk_f32_fp4 v[182:183], v27, 1.0 op_sel:[1,1,0]
	v_pk_fma_f32 v[184:185], v[30:31], v[188:189], v[184:185] op_sel_hi:[0,1,1]
	v_pk_fma_f32 v[30:31], v[30:31], v[182:183], v[160:161] op_sel_hi:[0,1,1]
	v_cvt_scalef32_pk_f32_fp4 v[182:183], v20, 1.0 op_sel:[1,0,0]
	s_waitcnt lgkmcnt(0)
	v_pk_fma_f32 v[164:165], v[26:27], v[182:183], v[164:165] op_sel_hi:[0,1,1]
	v_cvt_scalef32_pk_f32_fp4 v[182:183], v20, 1.0 op_sel:[0,1,0]
	v_pk_fma_f32 v[168:169], v[26:27], v[182:183], v[168:169] op_sel_hi:[0,1,1]
	v_cvt_scalef32_pk_f32_fp4 v[182:183], v20, 1.0 op_sel:[1,1,0]
	v_pk_fma_f32 v[172:173], v[26:27], v[182:183], v[172:173] op_sel_hi:[0,1,1]
	v_cvt_scalef32_pk_f32_fp4 v[182:183], v21, 1.0
	v_pk_fma_f32 v[176:177], v[26:27], v[182:183], v[176:177] op_sel_hi:[0,1,1]
	v_cvt_scalef32_pk_f32_fp4 v[182:183], v21, 1.0 op_sel:[1,0,0]
	v_cvt_scalef32_pk_f32_fp4 v[160:161], v20, 1.0
	v_pk_fma_f32 v[180:181], v[26:27], v[182:183], v[180:181] op_sel_hi:[0,1,1]
	v_cvt_scalef32_pk_f32_fp4 v[182:183], v21, 1.0 op_sel:[0,1,0]
	v_cvt_scalef32_pk_f32_fp4 v[20:21], v21, 1.0 op_sel:[1,1,0]
	v_pk_fma_f32 v[20:21], v[26:27], v[20:21], v[24:25] op_sel_hi:[0,1,1]
	v_cvt_scalef32_pk_f32_fp4 v[24:25], v22, 1.0
	v_pk_fma_f32 v[24:25], v[26:27], v[24:25], v[28:29] op_sel_hi:[0,1,1]
	v_cvt_scalef32_pk_f32_fp4 v[28:29], v22, 1.0 op_sel:[1,0,0]
	v_pk_fma_f32 v[28:29], v[26:27], v[28:29], v[158:159] op_sel_hi:[0,1,1]
	v_cvt_scalef32_pk_f32_fp4 v[158:159], v22, 1.0 op_sel:[0,1,0]
	v_pk_fma_f32 v[158:159], v[26:27], v[158:159], v[162:163] op_sel_hi:[0,1,1]
	v_cvt_scalef32_pk_f32_fp4 v[162:163], v22, 1.0 op_sel:[1,1,0]
	v_pk_fma_f32 v[162:163], v[26:27], v[162:163], v[166:167] op_sel_hi:[0,1,1]
	v_cvt_scalef32_pk_f32_fp4 v[166:167], v23, 1.0
	ds_bpermute_b32 v22, v220, v190
	v_pk_fma_f32 v[166:167], v[26:27], v[166:167], v[170:171] op_sel_hi:[0,1,1]
	v_cvt_scalef32_pk_f32_fp4 v[170:171], v23, 1.0 op_sel:[1,0,0]
	v_pk_fma_f32 v[170:171], v[26:27], v[170:171], v[174:175] op_sel_hi:[0,1,1]
	v_cvt_scalef32_pk_f32_fp4 v[174:175], v23, 1.0 op_sel:[0,1,0]
	v_pk_fma_f32 v[174:175], v[26:27], v[174:175], v[178:179] op_sel_hi:[0,1,1]
	v_cvt_scalef32_pk_f32_fp4 v[178:179], v23, 1.0 op_sel:[1,1,0]
	v_pk_fma_f32 v[160:161], v[160:161], v[26:27], v[186:187] op_sel_hi:[1,0,1]
	v_pk_fma_f32 v[182:183], v[26:27], v[182:183], v[184:185] op_sel_hi:[0,1,1]
	v_pk_fma_f32 v[26:27], v[26:27], v[178:179], v[30:31] op_sel_hi:[0,1,1]
	v_cvt_scalef32_pk_f32_fp4 v[30:31], v16, 1.0
	s_waitcnt lgkmcnt(0)
; DI void axpyV(f32x2 (&f2)[16], float a, const VRow& q) { axpy32r(f2, a, dec6(q)); }
; #define PEER_SWAP() do { _Pragma("unroll") for (int q_ = 0; q_ < 8; ++q_) _Pragma("unroll") for (int c_ = 0; c_ < 4; ++c_) { \
;             const auto r_ = __builtin_amdgcn_permlane32_swap(ra[q_][c_], rb[q_][c_], false, false); ucur[q_][c_] = r_[0]; vcur[q_][c_] = r_[1]; } } while (0)
; DI void axpyV(f32x2 (&f2)[16], float a, const VRow& q) {
;     const f32x2 aa = {a, a};
; #pragma unroll
;     for (int d = 0; d < 4; ++d) {
;         f2[4 * d] += aa * __builtin_amdgcn_cvt_scalef32_pk_f32_fp4(q[d], 1.0f, 0);     f2[4 * d + 1] += aa * __builtin_amdgcn_cvt_scalef32_pk_f32_fp4(q[d], 1.0f, 1);
;         f2[4 * d + 2] += aa * __builtin_amdgcn_cvt_scalef32_pk_f32_fp4(q[d], 1.0f, 2); f2[4 * d + 3] += aa * __builtin_amdgcn_cvt_scalef32_pk_f32_fp4(q[d], 1.0f, 3);
;     }
; }
; DI void peer_phase(const Params& p, int layer, bool dry) {
;     ...
; #pragma unroll
;             for (int q = 0; q < 8; ++q) { const float a = __shfl(act, (lane & 32) | ((q >> 2) << 4) | (((q >> 1) & 1) << 3) | ((q & 1) << 2)); axpyV(f2, a, vcur[q]); }
;             PEER_SWAP();
	v_pk_fma_f32 v[30:31], v[30:31], v[22:23], v[160:161] op_sel_hi:[1,0,1]
	v_cvt_scalef32_pk_f32_fp4 v[160:161], v16, 1.0 op_sel:[1,0,0]
	v_pk_fma_f32 v[160:161], v[22:23], v[160:161], v[164:165] op_sel_hi:[0,1,1]
	v_cvt_scalef32_pk_f32_fp4 v[164:165], v16, 1.0 op_sel:[0,1,0]
	v_pk_fma_f32 v[164:165], v[22:23], v[164:165], v[168:169] op_sel_hi:[0,1,1]
	v_cvt_scalef32_pk_f32_fp4 v[168:169], v16, 1.0 op_sel:[1,1,0]
	v_pk_fma_f32 v[168:169], v[22:23], v[168:169], v[172:173] op_sel_hi:[0,1,1]
	v_cvt_scalef32_pk_f32_fp4 v[172:173], v17, 1.0
	v_pk_fma_f32 v[172:173], v[22:23], v[172:173], v[176:177] op_sel_hi:[0,1,1]
	v_cvt_scalef32_pk_f32_fp4 v[176:177], v17, 1.0 op_sel:[1,0,0]
	v_cvt_scalef32_pk_f32_fp4 v[178:179], v17, 1.0 op_sel:[0,1,0]
	v_cvt_scalef32_pk_f32_fp4 v[16:17], v17, 1.0 op_sel:[1,1,0]
	v_pk_fma_f32 v[16:17], v[22:23], v[16:17], v[20:21] op_sel_hi:[0,1,1]
	v_cvt_scalef32_pk_f32_fp4 v[20:21], v18, 1.0
	v_pk_fma_f32 v[20:21], v[22:23], v[20:21], v[24:25] op_sel_hi:[0,1,1]
	v_cvt_scalef32_pk_f32_fp4 v[24:25], v18, 1.0 op_sel:[1,0,0]
	v_pk_fma_f32 v[24:25], v[22:23], v[24:25], v[28:29] op_sel_hi:[0,1,1]
	v_cvt_scalef32_pk_f32_fp4 v[28:29], v18, 1.0 op_sel:[0,1,0]
	v_pk_fma_f32 v[28:29], v[22:23], v[28:29], v[158:159] op_sel_hi:[0,1,1]
	v_cvt_scalef32_pk_f32_fp4 v[158:159], v18, 1.0 op_sel:[1,1,0]
	v_pk_fma_f32 v[158:159], v[22:23], v[158:159], v[162:163] op_sel_hi:[0,1,1]
	v_cvt_scalef32_pk_f32_fp4 v[162:163], v19, 1.0
	ds_bpermute_b32 v18, v221, v190
	v_pk_fma_f32 v[162:163], v[22:23], v[162:163], v[166:167] op_sel_hi:[0,1,1]
	v_cvt_scalef32_pk_f32_fp4 v[166:167], v19, 1.0 op_sel:[1,0,0]
	v_pk_fma_f32 v[166:167], v[22:23], v[166:167], v[170:171] op_sel_hi:[0,1,1]
	v_cvt_scalef32_pk_f32_fp4 v[170:171], v19, 1.0 op_sel:[0,1,0]
	v_pk_fma_f32 v[170:171], v[22:23], v[170:171], v[174:175] op_sel_hi:[0,1,1]
	v_cvt_scalef32_pk_f32_fp4 v[174:175], v19, 1.0 op_sel:[1,1,0]
	v_pk_fma_f32 v[176:177], v[22:23], v[176:177], v[180:181] op_sel_hi:[0,1,1]
	v_pk_fma_f32 v[178:179], v[22:23], v[178:179], v[182:183] op_sel_hi:[0,1,1]
	v_pk_fma_f32 v[22:23], v[22:23], v[174:175], v[26:27] op_sel_hi:[0,1,1]
	v_cvt_scalef32_pk_f32_fp4 v[26:27], v12, 1.0
	s_waitcnt lgkmcnt(0)
	v_pk_fma_f32 v[26:27], v[26:27], v[18:19], v[30:31] op_sel_hi:[1,0,1]
	v_cvt_scalef32_pk_f32_fp4 v[30:31], v12, 1.0 op_sel:[1,0,0]
	v_pk_fma_f32 v[30:31], v[18:19], v[30:31], v[160:161] op_sel_hi:[0,1,1]
	v_cvt_scalef32_pk_f32_fp4 v[160:161], v12, 1.0 op_sel:[0,1,0]
	v_pk_fma_f32 v[160:161], v[18:19], v[160:161], v[164:165] op_sel_hi:[0,1,1]
	v_cvt_scalef32_pk_f32_fp4 v[164:165], v12, 1.0 op_sel:[1,1,0]
	v_pk_fma_f32 v[164:165], v[18:19], v[164:165], v[168:169] op_sel_hi:[0,1,1]
	v_cvt_scalef32_pk_f32_fp4 v[168:169], v13, 1.0
	v_pk_fma_f32 v[168:169], v[18:19], v[168:169], v[172:173] op_sel_hi:[0,1,1]
	v_cvt_scalef32_pk_f32_fp4 v[172:173], v13, 1.0 op_sel:[1,0,0]
	v_cvt_scalef32_pk_f32_fp4 v[174:175], v13, 1.0 op_sel:[0,1,0]
	v_cvt_scalef32_pk_f32_fp4 v[12:13], v13, 1.0 op_sel:[1,1,0]
	v_pk_fma_f32 v[12:13], v[18:19], v[12:13], v[16:17] op_sel_hi:[0,1,1]
	v_cvt_scalef32_pk_f32_fp4 v[16:17], v14, 1.0
	v_pk_fma_f32 v[16:17], v[18:19], v[16:17], v[20:21] op_sel_hi:[0,1,1]
	v_cvt_scalef32_pk_f32_fp4 v[20:21], v14, 1.0 op_sel:[1,0,0]
	v_pk_fma_f32 v[20:21], v[18:19], v[20:21], v[24:25] op_sel_hi:[0,1,1]
	v_cvt_scalef32_pk_f32_fp4 v[24:25], v14, 1.0 op_sel:[0,1,0]
	v_pk_fma_f32 v[24:25], v[18:19], v[24:25], v[28:29] op_sel_hi:[0,1,1]
	v_cvt_scalef32_pk_f32_fp4 v[28:29], v14, 1.0 op_sel:[1,1,0]
	v_pk_fma_f32 v[28:29], v[18:19], v[28:29], v[158:159] op_sel_hi:[0,1,1]
	v_cvt_scalef32_pk_f32_fp4 v[158:159], v15, 1.0
	ds_bpermute_b32 v14, v222, v190
	v_pk_fma_f32 v[158:159], v[18:19], v[158:159], v[162:163] op_sel_hi:[0,1,1]
	v_cvt_scalef32_pk_f32_fp4 v[162:163], v15, 1.0 op_sel:[1,0,0]
	v_pk_fma_f32 v[162:163], v[18:19], v[162:163], v[166:167] op_sel_hi:[0,1,1]
	v_cvt_scalef32_pk_f32_fp4 v[166:167], v15, 1.0 op_sel:[0,1,0]
	v_pk_fma_f32 v[166:167], v[18:19], v[166:167], v[170:171] op_sel_hi:[0,1,1]
	v_cvt_scalef32_pk_f32_fp4 v[170:171], v15, 1.0 op_sel:[1,1,0]
	v_pk_fma_f32 v[172:173], v[18:19], v[172:173], v[176:177] op_sel_hi:[0,1,1]
	v_pk_fma_f32 v[174:175], v[18:19], v[174:175], v[178:179] op_sel_hi:[0,1,1]
	v_pk_fma_f32 v[18:19], v[18:19], v[170:171], v[22:23] op_sel_hi:[0,1,1]
	v_cvt_scalef32_pk_f32_fp4 v[22:23], v8, 1.0
	s_waitcnt lgkmcnt(0)
	v_pk_fma_f32 v[22:23], v[22:23], v[14:15], v[26:27] op_sel_hi:[1,0,1]
	v_cvt_scalef32_pk_f32_fp4 v[26:27], v8, 1.0 op_sel:[1,0,0]
	v_pk_fma_f32 v[26:27], v[14:15], v[26:27], v[30:31] op_sel_hi:[0,1,1]
	v_cvt_scalef32_pk_f32_fp4 v[30:31], v8, 1.0 op_sel:[0,1,0]
	v_pk_fma_f32 v[30:31], v[14:15], v[30:31], v[160:161] op_sel_hi:[0,1,1]
	v_cvt_scalef32_pk_f32_fp4 v[160:161], v8, 1.0 op_sel:[1,1,0]
	v_pk_fma_f32 v[160:161], v[14:15], v[160:161], v[164:165] op_sel_hi:[0,1,1]
	v_cvt_scalef32_pk_f32_fp4 v[164:165], v9, 1.0
	v_pk_fma_f32 v[164:165], v[14:15], v[164:165], v[168:169] op_sel_hi:[0,1,1]
	v_cvt_scalef32_pk_f32_fp4 v[168:169], v9, 1.0 op_sel:[1,0,0]
	v_cvt_scalef32_pk_f32_fp4 v[170:171], v9, 1.0 op_sel:[0,1,0]
	v_cvt_scalef32_pk_f32_fp4 v[8:9], v9, 1.0 op_sel:[1,1,0]
	v_pk_fma_f32 v[8:9], v[14:15], v[8:9], v[12:13] op_sel_hi:[0,1,1]
	v_cvt_scalef32_pk_f32_fp4 v[12:13], v10, 1.0
	v_pk_fma_f32 v[12:13], v[14:15], v[12:13], v[16:17] op_sel_hi:[0,1,1]
	v_cvt_scalef32_pk_f32_fp4 v[16:17], v10, 1.0 op_sel:[1,0,0]
	v_pk_fma_f32 v[16:17], v[14:15], v[16:17], v[20:21] op_sel_hi:[0,1,1]
	v_cvt_scalef32_pk_f32_fp4 v[20:21], v10, 1.0 op_sel:[0,1,0]
	v_pk_fma_f32 v[20:21], v[14:15], v[20:21], v[24:25] op_sel_hi:[0,1,1]
	v_cvt_scalef32_pk_f32_fp4 v[24:25], v10, 1.0 op_sel:[1,1,0]
	v_pk_fma_f32 v[24:25], v[14:15], v[24:25], v[28:29] op_sel_hi:[0,1,1]
	v_cvt_scalef32_pk_f32_fp4 v[28:29], v11, 1.0
	ds_bpermute_b32 v10, v223, v190
	v_pk_fma_f32 v[28:29], v[14:15], v[28:29], v[158:159] op_sel_hi:[0,1,1]
	v_cvt_scalef32_pk_f32_fp4 v[158:159], v11, 1.0 op_sel:[1,0,0]
	v_pk_fma_f32 v[158:159], v[14:15], v[158:159], v[162:163] op_sel_hi:[0,1,1]
	v_cvt_scalef32_pk_f32_fp4 v[162:163], v11, 1.0 op_sel:[0,1,0]
	v_pk_fma_f32 v[162:163], v[14:15], v[162:163], v[166:167] op_sel_hi:[0,1,1]
	v_cvt_scalef32_pk_f32_fp4 v[166:167], v11, 1.0 op_sel:[1,1,0]
	v_pk_fma_f32 v[168:169], v[14:15], v[168:169], v[172:173] op_sel_hi:[0,1,1]
	v_pk_fma_f32 v[170:171], v[14:15], v[170:171], v[174:175] op_sel_hi:[0,1,1]
	v_pk_fma_f32 v[14:15], v[14:15], v[166:167], v[18:19] op_sel_hi:[0,1,1]
	v_cvt_scalef32_pk_f32_fp4 v[18:19], v4, 1.0
	s_waitcnt lgkmcnt(0)
; DI float dotU(const URow& q, const f32x2 (&x2)[16]) { return dot32r(dec6(q), x2); }
; DI void axpyV(f32x2 (&f2)[16], float a, const VRow& q) { axpy32r(f2, a, dec6(q)); }
; #define PEER_LOADREC_FROM(isrc_, lb_) do { \
;         _Pragma("unroll") for (int q_ = 0; q_ < 8; ++q_) { \
;             const int ia_ = __builtin_amdgcn_readlane(isrc_, (lb_) + 2 * q_), ib_ = __builtin_amdgcn_readlane(isrc_, (lb_) + 2 * q_ + 1); \
;             ra[q_] = *(const u32x4*)(REC + (size_t)ia_ * 1024); rb[q_] = *(const u32x4*)(REC + (size_t)ib_ * 1024); } } while (0)
; #define PEER_SWAP() do { _Pragma("unroll") for (int q_ = 0; q_ < 8; ++q_) _Pragma("unroll") for (int c_ = 0; c_ < 4; ++c_) { \
;             const auto r_ = __builtin_amdgcn_permlane32_swap(ra[q_][c_], rb[q_][c_], false, false); ucur[q_][c_] = r_[0]; vcur[q_][c_] = r_[1]; } } while (0)
; DI void peer_phase(const Params& p, int layer, bool dry) {
;     ...
;         for (int bt = 0; bt < 8; ++bt) {
;             if (bt < 7) { const int nb = bt + 1; const int isrc = (nb < 4) ? iv0 : iv1; const int lb = (nb & 3) * 16; PEER_LOADREC_FROM(isrc, lb); }
;             else PEER_LOADREC_MEM(eidx + (size_t)tn * 128);
;             const int myidx = __shfl((bt < 4) ? iv0 : iv1, (bt & 3) * 16 + esel16);
;             const float gsc = __shfl((bt < 4) ? gv0 : gv1, (bt & 3) * 16 + esel16) * SV[myidx], usc = SU[myidx];
;             float d[8];
; #pragma unroll
;             for (int q = 0; q < 8; ++q) d[q] = dotU(ucur[q], x2);
;             float r4[4], r2[2], r1;
; #pragma unroll
;             for (int j = 0; j < 4; ++j) { const float send = b4 ? d[j] : d[j + 4], keep = b4 ? d[j + 4] : d[j]; r4[j] = keep + __shfl_xor(send, 16); }
; #pragma unroll
;             for (int j = 0; j < 2; ++j) { const float send = b3 ? r4[j] : r4[j + 2], keep = b3 ? r4[j + 2] : r4[j]; r2[j] = keep + __shfl_xor(send, 8); }
;             { const float send = b2_ ? r2[0] : r2[1], keep = b2_ ? r2[1] : r2[0]; r1 = keep + __shfl_xor(send, 4); }
;             r1 += __shfl_xor(r1, 2); r1 += __shfl_xor(r1, 1);
;             const float act = gelu_tanh(r1 * usc) * gsc;
; #pragma unroll
;             for (int q = 0; q < 8; ++q) { const float a = __shfl(act, (lane & 32) | ((q >> 2) << 4) | (((q >> 1) & 1) << 3) | ((q & 1) << 2)); axpyV(f2, a, vcur[q]); }
;             PEER_SWAP();
	v_pk_fma_f32 v[188:189], v[18:19], v[10:11], v[22:23] op_sel_hi:[1,0,1]
	v_cvt_scalef32_pk_f32_fp4 v[18:19], v4, 1.0 op_sel:[1,0,0]
	v_cvt_scalef32_pk_f32_fp4 v[22:23], v4, 1.0 op_sel:[0,1,0]
	v_pk_fma_f32 v[18:19], v[10:11], v[18:19], v[26:27] op_sel_hi:[0,1,1]
	v_pk_fma_f32 v[22:23], v[10:11], v[22:23], v[30:31] op_sel_hi:[0,1,1]
	v_cvt_scalef32_pk_f32_fp4 v[26:27], v4, 1.0 op_sel:[1,1,0]
	v_cvt_scalef32_pk_f32_fp4 v[30:31], v5, 1.0
	v_pk_fma_f32 v[26:27], v[10:11], v[26:27], v[160:161] op_sel_hi:[0,1,1]
	v_pk_fma_f32 v[30:31], v[10:11], v[30:31], v[164:165] op_sel_hi:[0,1,1]
	v_cvt_scalef32_pk_f32_fp4 v[160:161], v5, 1.0 op_sel:[1,0,0]
	v_cvt_scalef32_pk_f32_fp4 v[164:165], v5, 1.0 op_sel:[0,1,0]
	v_cvt_scalef32_pk_f32_fp4 v[4:5], v5, 1.0 op_sel:[1,1,0]
	v_pk_fma_f32 v[4:5], v[10:11], v[4:5], v[8:9] op_sel_hi:[0,1,1]
	v_cvt_scalef32_pk_f32_fp4 v[8:9], v6, 1.0
	v_pk_fma_f32 v[8:9], v[10:11], v[8:9], v[12:13] op_sel_hi:[0,1,1]
	v_cvt_scalef32_pk_f32_fp4 v[12:13], v6, 1.0 op_sel:[1,0,0]
	v_pk_fma_f32 v[12:13], v[10:11], v[12:13], v[16:17] op_sel_hi:[0,1,1]
	v_cvt_scalef32_pk_f32_fp4 v[16:17], v6, 1.0 op_sel:[0,1,0]
	v_pk_fma_f32 v[16:17], v[10:11], v[16:17], v[20:21] op_sel_hi:[0,1,1]
	v_cvt_scalef32_pk_f32_fp4 v[20:21], v6, 1.0 op_sel:[1,1,0]
	ds_bpermute_b32 v190, v224, v190
	v_pk_fma_f32 v[20:21], v[10:11], v[20:21], v[24:25] op_sel_hi:[0,1,1]
	v_cvt_scalef32_pk_f32_fp4 v[24:25], v7, 1.0
	v_pk_fma_f32 v[24:25], v[10:11], v[24:25], v[28:29] op_sel_hi:[0,1,1]
	v_cvt_scalef32_pk_f32_fp4 v[28:29], v7, 1.0 op_sel:[1,0,0]
	v_pk_fma_f32 v[28:29], v[10:11], v[28:29], v[158:159] op_sel_hi:[0,1,1]
	v_cvt_scalef32_pk_f32_fp4 v[158:159], v7, 1.0 op_sel:[0,1,0]
	v_cvt_scalef32_pk_f32_fp4 v[6:7], v7, 1.0 op_sel:[1,1,0]
	v_pk_fma_f32 v[160:161], v[10:11], v[160:161], v[168:169] op_sel_hi:[0,1,1]
	v_pk_fma_f32 v[166:167], v[10:11], v[164:165], v[170:171] op_sel_hi:[0,1,1]
	v_pk_fma_f32 v[182:183], v[10:11], v[158:159], v[162:163] op_sel_hi:[0,1,1]
	v_pk_fma_f32 v[6:7], v[10:11], v[6:7], v[14:15] op_sel_hi:[0,1,1]
	v_cvt_scalef32_pk_f32_fp4 v[10:11], v0, 1.0 op_sel:[1,0,0]
	s_waitcnt lgkmcnt(0)
	v_pk_fma_f32 v[164:165], v[190:191], v[10:11], v[18:19] op_sel_hi:[0,1,1]
	v_cvt_scalef32_pk_f32_fp4 v[10:11], v0, 1.0 op_sel:[0,1,0]
	v_pk_fma_f32 v[168:169], v[190:191], v[10:11], v[22:23] op_sel_hi:[0,1,1]
	v_cvt_scalef32_pk_f32_fp4 v[10:11], v0, 1.0 op_sel:[1,1,0]
	v_pk_fma_f32 v[172:173], v[190:191], v[10:11], v[26:27] op_sel_hi:[0,1,1]
	v_cvt_scalef32_pk_f32_fp4 v[10:11], v1, 1.0
	v_pk_fma_f32 v[176:177], v[190:191], v[10:11], v[30:31] op_sel_hi:[0,1,1]
	v_cvt_scalef32_pk_f32_fp4 v[10:11], v1, 1.0 op_sel:[1,0,0]
	v_cvt_scalef32_pk_f32_fp4 v[228:229], v0, 1.0
	v_pk_fma_f32 v[180:181], v[190:191], v[10:11], v[160:161] op_sel_hi:[0,1,1]
	v_cvt_scalef32_pk_f32_fp4 v[10:11], v1, 1.0 op_sel:[0,1,0]
	v_cvt_scalef32_pk_f32_fp4 v[0:1], v1, 1.0 op_sel:[1,1,0]
	v_pk_fma_f32 v[186:187], v[190:191], v[0:1], v[4:5] op_sel_hi:[0,1,1]
	v_cvt_scalef32_pk_f32_fp4 v[0:1], v2, 1.0
	v_pk_fma_f32 v[158:159], v[190:191], v[0:1], v[8:9] op_sel_hi:[0,1,1]
	v_cvt_scalef32_pk_f32_fp4 v[0:1], v2, 1.0 op_sel:[1,0,0]
	v_pk_fma_f32 v[162:163], v[190:191], v[0:1], v[12:13] op_sel_hi:[0,1,1]
	v_cvt_scalef32_pk_f32_fp4 v[0:1], v2, 1.0 op_sel:[0,1,0]
	v_pk_fma_f32 v[184:185], v[190:191], v[10:11], v[166:167] op_sel_hi:[0,1,1]
	v_pk_fma_f32 v[166:167], v[190:191], v[0:1], v[16:17] op_sel_hi:[0,1,1]
	v_cvt_scalef32_pk_f32_fp4 v[0:1], v2, 1.0 op_sel:[1,1,0]
	v_pk_fma_f32 v[170:171], v[190:191], v[0:1], v[20:21] op_sel_hi:[0,1,1]
	v_cvt_scalef32_pk_f32_fp4 v[0:1], v3, 1.0
	v_pk_fma_f32 v[174:175], v[190:191], v[0:1], v[24:25] op_sel_hi:[0,1,1]
	v_cvt_scalef32_pk_f32_fp4 v[0:1], v3, 1.0 op_sel:[1,0,0]
	v_pk_fma_f32 v[178:179], v[190:191], v[0:1], v[28:29] op_sel_hi:[0,1,1]
	v_cvt_scalef32_pk_f32_fp4 v[0:1], v3, 1.0 op_sel:[0,1,0]
	v_pk_fma_f32 v[182:183], v[190:191], v[0:1], v[182:183] op_sel_hi:[0,1,1]
	v_cvt_scalef32_pk_f32_fp4 v[0:1], v3, 1.0 op_sel:[1,1,0]
	v_pk_fma_f32 v[160:161], v[190:191], v[0:1], v[6:7] op_sel_hi:[0,1,1]
	s_waitcnt vmcnt(0)
	ds_read_b128 v[60:63], v196
	ds_read_b128 v[28:31], v233 offset:512
	ds_read_b128 v[56:59], v196 offset:64
	ds_read_b128 v[24:27], v233 offset:2592
	ds_read_b128 v[52:55], v196 offset:128
	ds_read_b128 v[20:23], v233 offset:4672
	ds_read_b128 v[48:51], v196 offset:192
	ds_read_b128 v[16:19], v233 offset:6752
	ds_read_b128 v[44:47], v196 offset:256
	ds_read_b128 v[12:15], v233 offset:8832
	ds_read_b128 v[40:43], v196 offset:320
	ds_read_b128 v[8:11], v233 offset:10912
	ds_read_b128 v[36:39], v196 offset:384
	ds_read_b128 v[4:7], v233 offset:12992
	ds_read_b128 v[32:35], v196 offset:448
	ds_read_b128 v[0:3], v233 offset:15072
	s_waitcnt lgkmcnt(0)
	v_pk_fma_f32 v[188:189], v[228:229], v[190:191], v[188:189] op_sel_hi:[1,0,1]
	s_cbranch_scc1 .LBB0_40
.LBB0_36:
	s_cmpk_lg_i32 s21, 0x70
	s_mov_b64 s[72:73], -1
	s_cbranch_scc0 .LBB0_38
	s_cmp_lt_u32 s11, 3
	s_cselect_b64 vcc, -1, 0
	s_waitcnt vmcnt(6)
	v_cndmask_b32_e32 v64, v225, v218, vcc
	s_add_i32 s29, s21, 18
	v_readlane_b32 s30, v64, s29
	s_add_i32 s29, s21, 19
	v_readlane_b32 s40, v64, s29
	s_add_i32 s29, s21, 20
	v_readlane_b32 s34, v64, s29
	s_add_i32 s29, s21, 21
	v_readlane_b32 s38, v64, s29
	s_add_i32 s29, s21, 22
	v_readlane_b32 s50, v64, s29
	s_add_i32 s29, s21, 23
	v_readlane_b32 s48, v64, s29
	s_add_i32 s29, s21, 24
	v_readlane_b32 s54, v64, s29
	s_add_i32 s29, s21, 25
	v_readlane_b32 s46, v64, s29
	s_add_i32 s29, s21, 26
	v_readlane_b32 s58, v64, s29
	s_add_i32 s29, s21, 27
	v_readlane_b32 s36, v64, s29
	s_add_i32 s29, s21, 28
	v_readlane_b32 s62, v64, s29
	s_add_i32 s29, s21, 29
	v_readlane_b32 s52, v64, s29
	s_add_i32 s29, s21, 30
	s_add_i32 s27, s21, 16
	s_add_i32 s26, s21, 17
	v_readlane_b32 s64, v64, s29
	s_add_i32 s29, s21, 31
	v_readlane_b32 s28, v64, s27
	v_readlane_b32 s26, v64, s26
	v_readlane_b32 s56, v64, s29
	s_and_b32 s60, s21, 48
	s_mov_b64 s[72:73], 0
	s_mov_b32 s21, s27

; #define PEER_SWAP() do { _Pragma("unroll") for (int q_ = 0; q_ < 8; ++q_) _Pragma("unroll") for (int c_ = 0; c_ < 4; ++c_) { \
;             const auto r_ = __builtin_amdgcn_permlane32_swap(ra[q_][c_], rb[q_][c_], false, false); ucur[q_][c_] = r_[0]; vcur[q_][c_] = r_[1]; } } while (0)
; #define PEER_LOADREC_MEM(ep_) do { \
;         _Pragma("unroll") for (int q_ = 0; q_ < 8; ++q_) { \
;             const int ia_ = __builtin_amdgcn_readfirstlane((ep_)[2 * q_]), ib_ = __builtin_amdgcn_readfirstlane((ep_)[2 * q_ + 1]); \
;             ra[q_] = *(const u32x4*)(REC + (size_t)ia_ * 1024); rb[q_] = *(const u32x4*)(REC + (size_t)ib_ * 1024); } } while (0)
; #define PEER_NEXTOPS(t_) do { const u32x4* xr_ = (const u32x4*)(xb + (size_t)(t_) * PA + 32 * l5); xq[0] = xr_[0]; xq[1] = xr_[1]; xq[2] = xr_[2]; xq[3] = xr_[3]; \
;         ivq0 = eidx[(size_t)(t_) * 128 + lane]; ivq1 = eidx[(size_t)(t_) * 128 + 64 + lane]; gvq0 = gate[(size_t)(t_) * 128 + lane]; gvq1 = gate[(size_t)(t_) * 128 + 64 + lane]; } while (0)
; DI void peer_phase(const Params& p, int layer, bool dry) {
;     ...
;     if (gw < T_TOK) {
;         PEER_LOADREC_MEM(eidx + (size_t)gw * 128);
;         PEER_SWAP();
;     }
;     u32x4 xq[4]; int ivq0 = 0, ivq1 = 0; float gvq0 = 0.f, gvq1 = 0.f;
;     ...
;     if (gw < T_TOK) PEER_NEXTOPS(gw);
;     for (int t = gw; t < T_TOK; t += nw) {
.LBB0_50:
	v_mov_b64_e32 v[130:131], 0x400
	v_mov_b64_e32 v[132:133], 0x3ff
	v_mov_b64_e32 v[134:135], 0x200
	v_mov_b64_e32 v[136:137], 0x1ff
	v_mov_b64_e32 v[138:139], 0x480
	v_mov_b64_e32 v[140:141], 0x47f
	v_mov_b32_e32 v206, 1
	v_mov_b32_e32 v207, 2
	v_mov_b32_e32 v208, 6
	v_mov_b32_e32 v209, 64
	v_mov_b32_e32 v196, 0x260
	v_mov_b32_e32 v210, 0x1200
	s_mov_b64 s[0:1], 0
	s_mov_b32 s28, s43

; __global__ void __launch_bounds__(512) fwd_kernel(Params p) {
;     extern __shared__ __attribute__((aligned(16))) unsigned char smem[];
	.amdhsa_kernel _Z10fwd_kernel6Params
		.amdhsa_group_segment_fixed_size 6144
		.amdhsa_private_segment_fixed_size 0
		.amdhsa_kernarg_size 424
		.amdhsa_user_sgpr_count 2
		.amdhsa_user_sgpr_dispatch_ptr 0
		.amdhsa_user_sgpr_queue_ptr 0
		.amdhsa_user_sgpr_kernarg_segment_ptr 1
		.amdhsa_user_sgpr_dispatch_id 0
		.amdhsa_user_sgpr_kernarg_preload_length 0
		.amdhsa_user_sgpr_kernarg_preload_offset 0
		.amdhsa_user_sgpr_private_segment_size 0
		.amdhsa_uses_dynamic_stack 0
		.amdhsa_enable_private_segment 0
		.amdhsa_system_sgpr_workgroup_id_x 1
		.amdhsa_system_sgpr_workgroup_id_y 0
		.amdhsa_system_sgpr_workgroup_id_z 0
		.amdhsa_system_sgpr_workgroup_info 0
		.amdhsa_system_vgpr_workitem_id 2
		.amdhsa_next_free_vgpr 253
		.amdhsa_next_free_sgpr 98
		.amdhsa_accum_offset 256
		.amdhsa_reserve_vcc 1
		.amdhsa_float_round_mode_32 0
		.amdhsa_float_round_mode_16_64 0
		.amdhsa_float_denorm_mode_32 3
		.amdhsa_float_denorm_mode_16_64 3
		.amdhsa_dx10_clamp 1
		.amdhsa_ieee_mode 1
		.amdhsa_fp16_overflow 0
		.amdhsa_tg_split 0
		.amdhsa_exception_fp_ieee_invalid_op 0
		.amdhsa_exception_fp_denorm_src 0
		.amdhsa_exception_fp_ieee_div_zero 0
		.amdhsa_exception_fp_ieee_overflow 0
		.amdhsa_exception_fp_ieee_underflow 0
		.amdhsa_exception_fp_ieee_inexact 0
		.amdhsa_exception_int_div_zero 0
	.end_amdhsa_kernel

; __global__ void __launch_bounds__(512) fwd_kernel(Params p) {
;     extern __shared__ __attribute__((aligned(16))) unsigned char smem[];
amdhsa.kernels:
  - .agpr_count:     0
    .args:
      - .offset:         0
        .size:           168
        .value_kind:     by_value
      - .offset:         168
        .size:           4
        .value_kind:     hidden_block_count_x
      - .offset:         172
        .size:           4
        .value_kind:     hidden_block_count_y
      - .offset:         176
        .size:           4
        .value_kind:     hidden_block_count_z
      - .offset:         180
        .size:           2
        .value_kind:     hidden_group_size_x
      - .offset:         182
        .size:           2
        .value_kind:     hidden_group_size_y
      - .offset:         184
        .size:           2
        .value_kind:     hidden_group_size_z
      - .offset:         186
        .size:           2
        .value_kind:     hidden_remainder_x
      - .offset:         188
        .size:           2
        .value_kind:     hidden_remainder_y
      - .offset:         190
        .size:           2
        .value_kind:     hidden_remainder_z
      - .offset:         208
        .size:           8
        .value_kind:     hidden_global_offset_x
      - .offset:         216
        .size:           8
        .value_kind:     hidden_global_offset_y
      - .offset:         224
        .size:           8
        .value_kind:     hidden_global_offset_z
      - .offset:         232
        .size:           2
        .value_kind:     hidden_grid_dims
      - .offset:         256
        .size:           8
        .value_kind:     hidden_multigrid_sync_arg
      - .offset:         288
        .size:           4
        .value_kind:     hidden_dynamic_lds_size
    .group_segment_fixed_size: 6144
    .kernarg_segment_align: 8
    .kernarg_segment_size: 424
    .language:       OpenCL C
    .language_version:
      - 2
      - 0
    .max_flat_workgroup_size: 512
    .name:           _Z10fwd_kernel6Params
    .private_segment_fixed_size: 0
    .sgpr_count:     104
    .sgpr_spill_count: 157
    .symbol:         _Z10fwd_kernel6Params.kd
    .uniform_work_group_size: 1
    .uses_dynamic_stack: false
    .vgpr_count:     253
    .vgpr_spill_count: 0
    .wavefront_size: 64
